# GEMM K-loop: removed the lgkmcnt(8) pacing wait in front of the mid barrier of phases 1 and 5 (the lgkmcnt(0) after the barrier still guards the reads)
# baseline (speedup 1.0000x reference)
; #define PG8_STAGE(bufoff, gbase, voff) do { _Pragma("unroll") for (int _i = 0; _i < 2; ++_i) \
;         __builtin_amdgcn_global_load_lds((const unsigned*)((const char*)(gbase) + (voff)[_i]), (LAS unsigned*)(lds + (bufoff) + ldsw + _i * 8192), 16, 0, 0); } while (0)
; #define PG8_LDA(dst, b, h) do { _Pragma("unroll") for (int m = 0; m < 4; ++m) _Pragma("unroll") for (int k = 0; k < 2; ++k) dst[m][k] = *(const LAS bf16x8*)(lds + PG8_SA(b, h) + aoff + m * 2048 + k * 1024); } while (0)
; #define PG8_LDB(dst, b, h) do { _Pragma("unroll") for (int n = 0; n < 2; ++n) _Pragma("unroll") for (int k = 0; k < 2; ++k) dst[n][k] = *(const LAS bf16x8*)(lds + PG8_SB(b, h) + boff + n * 2048 + k * 1024); } while (0)
; #define PG8_MMA(ai, bj, At, Bt) do { __builtin_amdgcn_s_setprio(1); _Pragma("unroll") for (int m = 0; m < 4; ++m) _Pragma("unroll") for (int n = 0; n < 2; ++n) _Pragma("unroll") for (int k = 0; k < 2; ++k) \
;         acc[ai][bj][m][n] = __builtin_amdgcn_mfma_f32_16x16x32_bf16(Bt[n][k], At[m][k], acc[ai][bj][m][n], 0, 0, 0); __builtin_amdgcn_s_setprio(0); } while (0)
; #define PG8_WAIT_L(n) asm volatile("s_waitcnt lgkmcnt(" #n ")" ::: "memory")
; #define PG8_BAR __builtin_amdgcn_s_barrier()
; #define PG8_SCHED __builtin_amdgcn_sched_barrier(0)
; template <class Epi, class Sched>
; __device__ __forceinline__ void gemm_phase(LAS unsigned char* lds, const Gemm g, const Sched& S, const Epi& E) {
;     ...
;         for (int t = 0; t < nt; t += 2) {
;             const bool last = (t == nt - 2);
;             const char* a1 = cA + (size_t)(t + 1) * kstep;
;             const char* a2 = last ? nA : cA + (size_t)(t + 2) * kstep; const char* b2 = last ? nB : cB + (size_t)(t + 2) * kstep;
;             const char* a3 = a2 + kstep; const char* b3 = b2 + kstep;
;             if (last && has_next) S.a_ready(nxt);
;             PG8_LDB(B0, 0, 0); PG8_SCHED; PG8_LDA(At, 0, 0); PG8_STAGE(PG8_SA(1, 1), a1 + hstep, voffA);
;             PG8_WAIT_L(8); PG8_BAR; PG8_WAIT_L(0); PG8_MMA(0, 0, At, B0); PG8_BAR; PG8_SCHED;
;             PG8_LDB(B1, 0, 1); PG8_STAGE(PG8_SB(0, 0), b2, voffB);
;             PG8_BAR; PG8_WAIT_L(0); PG8_MMA(0, 1, At, B1); PG8_BAR;
;             PG8_LDA(At, 0, 1); PG8_STAGE(PG8_SA(0, 0), a2, voffA);
;             PG8_BAR; PG8_WAIT_L(0); PG8_MMA(1, 0, At, B0); PG8_BAR; PG8_SCHED;
.LBB0_187:
	s_add_u32 s20, s72, 0xfffc0080
	s_addc_u32 s21, s73, -1
	s_add_i32 s22, 16, 0x10000
	v_add_u32_e32 v153, s22, v154
	ds_read_b128 v[156:159], v153
	ds_read_b128 v[160:163], v153 offset:1024
	ds_read_b128 v[164:167], v153 offset:2048
	ds_read_b128 v[168:171], v153 offset:3072
	s_cmp_eq_u32 s19, 12
	s_cselect_b32 s71, s41, s21
	s_cselect_b32 s70, s78, s20
	s_cselect_b32 s67, s1, s18
	s_cselect_b32 s66, s16, s17
	v_lshl_add_u64 v[216:217], s[72:73], 0, v[148:149]
	s_add_i32 m0, s9, 0xc000
	ds_read_b128 v[172:175], v155
	ds_read_b128 v[188:191], v155 offset:1024
	ds_read_b128 v[192:195], v155 offset:2048
	ds_read_b128 v[196:199], v155 offset:3072
	ds_read_b128 v[200:203], v155 offset:4096
	ds_read_b128 v[204:207], v155 offset:5120
	ds_read_b128 v[208:211], v155 offset:6144
	ds_read_b128 v[212:215], v155 offset:7168
	global_load_lds_dwordx4 v[216:217], off
	v_lshl_add_u64 v[216:217], s[72:73], 0, v[150:151]
	s_add_i32 m0, s9, 0xe000
	s_nop 0
	global_load_lds_dwordx4 v[216:217], off
	s_barrier
	s_waitcnt lgkmcnt(0)
	s_setprio 1
	s_waitcnt lgkmcnt(0)
	v_mfma_f32_16x16x32_bf16 v[126:129], v[156:159], v[172:175], v[126:129]
	v_mfma_f32_16x16x32_bf16 v[122:125], v[164:167], v[172:175], v[122:125]
	v_mfma_f32_16x16x32_bf16 v[118:121], v[156:159], v[192:195], v[118:121]
	v_mfma_f32_16x16x32_bf16 v[110:113], v[164:167], v[192:195], v[110:113]
	v_mfma_f32_16x16x32_bf16 v[102:105], v[156:159], v[200:203], v[102:105]
	v_mfma_f32_16x16x32_bf16 v[94:97], v[164:167], v[200:203], v[94:97]
	v_mfma_f32_16x16x32_bf16 v[86:89], v[156:159], v[208:211], v[86:89]
	v_mfma_f32_16x16x32_bf16 v[78:81], v[164:167], v[208:211], v[78:81]
	v_mfma_f32_16x16x32_bf16 v[126:129], v[160:163], v[188:191], v[126:129]
	v_mfma_f32_16x16x32_bf16 v[122:125], v[168:171], v[188:191], v[122:125]
	v_mfma_f32_16x16x32_bf16 v[118:121], v[160:163], v[196:199], v[118:121]
	v_mfma_f32_16x16x32_bf16 v[110:113], v[168:171], v[196:199], v[110:113]
	v_mfma_f32_16x16x32_bf16 v[102:105], v[160:163], v[204:207], v[102:105]
	v_mfma_f32_16x16x32_bf16 v[94:97], v[168:171], v[204:207], v[94:97]
	v_mfma_f32_16x16x32_bf16 v[86:89], v[160:163], v[212:215], v[86:89]
	v_mfma_f32_16x16x32_bf16 v[78:81], v[168:171], v[212:215], v[78:81]
	s_setprio 0
	s_barrier
	s_add_i32 s23, 16, 0x14000
	s_add_i32 s20, s22, s8
	v_add_u32_e32 v153, s23, v154
	v_lshl_add_u64 v[232:233], s[66:67], 0, v[144:145]
	s_mov_b32 m0, s20
	ds_read_b128 v[216:219], v153
	ds_read_b128 v[220:223], v153 offset:1024
	ds_read_b128 v[224:227], v153 offset:2048
	ds_read_b128 v[228:231], v153 offset:3072
	global_load_lds_dwordx4 v[232:233], off
	v_lshl_add_u64 v[234:235], s[66:67], 0, v[140:141]
	s_add_i32 m0, s20, 0x2000
	s_nop 0
	global_load_lds_dwordx4 v[234:235], off
	s_barrier
	s_waitcnt lgkmcnt(0)
	s_setprio 1
	s_waitcnt lgkmcnt(0)
	v_mfma_f32_16x16x32_bf16 v[114:117], v[216:219], v[172:175], v[114:117]
	v_mfma_f32_16x16x32_bf16 v[106:109], v[224:227], v[172:175], v[106:109]
	v_mfma_f32_16x16x32_bf16 v[98:101], v[216:219], v[192:195], v[98:101]
	v_mfma_f32_16x16x32_bf16 v[90:93], v[224:227], v[192:195], v[90:93]
	v_mfma_f32_16x16x32_bf16 v[82:85], v[216:219], v[200:203], v[82:85]
	v_mfma_f32_16x16x32_bf16 v[74:77], v[224:227], v[200:203], v[74:77]
	v_mfma_f32_16x16x32_bf16 v[70:73], v[216:219], v[208:211], v[70:73]
	v_mfma_f32_16x16x32_bf16 v[66:69], v[224:227], v[208:211], v[66:69]
	v_mfma_f32_16x16x32_bf16 v[114:117], v[220:223], v[188:191], v[114:117]
	v_mfma_f32_16x16x32_bf16 v[106:109], v[228:231], v[188:191], v[106:109]
	v_mfma_f32_16x16x32_bf16 v[98:101], v[220:223], v[196:199], v[98:101]
	v_mfma_f32_16x16x32_bf16 v[90:93], v[228:231], v[196:199], v[90:93]
	v_mfma_f32_16x16x32_bf16 v[82:85], v[220:223], v[204:207], v[82:85]
	v_mfma_f32_16x16x32_bf16 v[74:77], v[228:231], v[204:207], v[74:77]
	v_mfma_f32_16x16x32_bf16 v[70:73], v[220:223], v[212:215], v[70:73]
	v_mfma_f32_16x16x32_bf16 v[66:69], v[228:231], v[212:215], v[66:69]
	s_setprio 0
	s_mov_b32 m0, s9
	v_lshl_add_u64 v[236:237], s[70:71], 0, v[146:147]
	s_barrier
	ds_read_b128 v[172:175], v155 offset:16384
	ds_read_b128 v[188:191], v155 offset:17408
	ds_read_b128 v[192:195], v155 offset:18432
	ds_read_b128 v[196:199], v155 offset:19456
	ds_read_b128 v[200:203], v155 offset:20480
	ds_read_b128 v[204:207], v155 offset:21504
	ds_read_b128 v[208:211], v155 offset:22528
	ds_read_b128 v[212:215], v155 offset:23552
	global_load_lds_dwordx4 v[236:237], off
	v_lshl_add_u64 v[238:239], s[70:71], 0, v[142:143]
	s_mov_b32 m0, s10
	s_nop 0
	global_load_lds_dwordx4 v[238:239], off
	s_barrier
	s_waitcnt lgkmcnt(0)
	s_setprio 1
	s_waitcnt lgkmcnt(0)
	v_mfma_f32_16x16x32_bf16 v[62:65], v[156:159], v[172:175], v[62:65]
	v_mfma_f32_16x16x32_bf16 v[58:61], v[164:167], v[172:175], v[58:61]
	v_mfma_f32_16x16x32_bf16 v[54:57], v[156:159], v[192:195], v[54:57]
	v_mfma_f32_16x16x32_bf16 v[50:53], v[164:167], v[192:195], v[50:53]
	v_mfma_f32_16x16x32_bf16 v[38:41], v[156:159], v[200:203], v[38:41]
	v_mfma_f32_16x16x32_bf16 v[34:37], v[164:167], v[200:203], v[34:37]
	v_mfma_f32_16x16x32_bf16 v[22:25], v[156:159], v[208:211], v[22:25]
	v_mfma_f32_16x16x32_bf16 v[18:21], v[164:167], v[208:211], v[18:21]
	v_mfma_f32_16x16x32_bf16 v[62:65], v[160:163], v[188:191], v[62:65]
	v_mfma_f32_16x16x32_bf16 v[58:61], v[168:171], v[188:191], v[58:61]
	v_mfma_f32_16x16x32_bf16 v[54:57], v[160:163], v[196:199], v[54:57]
	v_mfma_f32_16x16x32_bf16 v[50:53], v[168:171], v[196:199], v[50:53]
	v_mfma_f32_16x16x32_bf16 v[38:41], v[160:163], v[204:207], v[38:41]
	v_mfma_f32_16x16x32_bf16 v[34:37], v[168:171], v[204:207], v[34:37]
	v_mfma_f32_16x16x32_bf16 v[22:25], v[160:163], v[212:215], v[22:25]
	v_mfma_f32_16x16x32_bf16 v[18:21], v[168:171], v[212:215], v[18:21]
	s_setprio 0
	s_barrier
; #define PG8_STAGE(bufoff, gbase, voff) do { _Pragma("unroll") for (int _i = 0; _i < 2; ++_i) \
;         __builtin_amdgcn_global_load_lds((const unsigned*)((const char*)(gbase) + (voff)[_i]), (LAS unsigned*)(lds + (bufoff) + ldsw + _i * 8192), 16, 0, 0); } while (0)
; #define PG8_LDA(dst, b, h) do { _Pragma("unroll") for (int m = 0; m < 4; ++m) _Pragma("unroll") for (int k = 0; k < 2; ++k) dst[m][k] = *(const LAS bf16x8*)(lds + PG8_SA(b, h) + aoff + m * 2048 + k * 1024); } while (0)
; #define PG8_LDB(dst, b, h) do { _Pragma("unroll") for (int n = 0; n < 2; ++n) _Pragma("unroll") for (int k = 0; k < 2; ++k) dst[n][k] = *(const LAS bf16x8*)(lds + PG8_SB(b, h) + boff + n * 2048 + k * 1024); } while (0)
; #define PG8_MMA(ai, bj, At, Bt) do { __builtin_amdgcn_s_setprio(1); _Pragma("unroll") for (int m = 0; m < 4; ++m) _Pragma("unroll") for (int n = 0; n < 2; ++n) _Pragma("unroll") for (int k = 0; k < 2; ++k) \
;         acc[ai][bj][m][n] = __builtin_amdgcn_mfma_f32_16x16x32_bf16(Bt[n][k], At[m][k], acc[ai][bj][m][n], 0, 0, 0); __builtin_amdgcn_s_setprio(0); } while (0)
; #define PG8_WAIT_V(n) asm volatile("s_waitcnt vmcnt(" #n ")" ::: "memory")
; #define PG8_WAIT_L(n) asm volatile("s_waitcnt lgkmcnt(" #n ")" ::: "memory")
; #define PG8_BAR __builtin_amdgcn_s_barrier()
; #define PG8_SCHED __builtin_amdgcn_sched_barrier(0)
; template <class Epi, class Sched>
; __device__ __forceinline__ void gemm_phase(LAS unsigned char* lds, const Gemm g, const Sched& S, const Epi& E) {
;     ...
;             PG8_STAGE(PG8_SB(0, 1), b2 + hstep, voffB);
;             PG8_WAIT_V(6); PG8_BAR; PG8_MMA(1, 1, At, B1); PG8_BAR;
;             PG8_LDB(B0, 1, 0); PG8_SCHED; PG8_LDA(At, 1, 0); PG8_STAGE(PG8_SA(0, 1), a2 + hstep, voffA);
;             PG8_WAIT_L(8); PG8_BAR; PG8_WAIT_L(0); PG8_MMA(0, 0, At, B0); PG8_BAR; PG8_SCHED;
;             PG8_LDB(B1, 1, 1); PG8_STAGE(PG8_SB(1, 0), b3, voffB);
;             PG8_BAR; PG8_WAIT_L(0); PG8_MMA(0, 1, At, B1); PG8_BAR;
;             PG8_LDA(At, 1, 1); PG8_STAGE(PG8_SA(1, 0), a3, voffA);
	s_add_u32 s20, s66, 0x40000
	s_addc_u32 s21, s67, 0
	s_add_i32 s22, s23, s8
	v_lshl_add_u64 v[156:157], s[20:21], 0, v[144:145]
	s_mov_b32 m0, s22
	s_nop 0
	global_load_lds_dwordx4 v[156:157], off
	v_lshl_add_u64 v[156:157], s[20:21], 0, v[140:141]
	s_add_i32 m0, s22, 0x2000
	s_nop 0
	global_load_lds_dwordx4 v[156:157], off
	s_waitcnt vmcnt(6)
	s_barrier
	s_setprio 1
	v_mfma_f32_16x16x32_bf16 v[46:49], v[216:219], v[172:175], v[46:49]
	v_mfma_f32_16x16x32_bf16 v[42:45], v[224:227], v[172:175], v[42:45]
	v_mfma_f32_16x16x32_bf16 v[30:33], v[216:219], v[192:195], v[30:33]
	v_mfma_f32_16x16x32_bf16 v[26:29], v[224:227], v[192:195], v[26:29]
	v_mfma_f32_16x16x32_bf16 v[14:17], v[216:219], v[200:203], v[14:17]
	v_mfma_f32_16x16x32_bf16 v[10:13], v[224:227], v[200:203], v[10:13]
	v_mfma_f32_16x16x32_bf16 v[4:7], v[216:219], v[208:211], v[4:7]
	v_mfma_f32_16x16x32_bf16 v[0:3], v[224:227], v[208:211], v[0:3]
	v_mfma_f32_16x16x32_bf16 v[46:49], v[220:223], v[188:191], v[46:49]
	v_mfma_f32_16x16x32_bf16 v[42:45], v[228:231], v[188:191], v[42:45]
	v_mfma_f32_16x16x32_bf16 v[30:33], v[220:223], v[196:199], v[30:33]
	v_mfma_f32_16x16x32_bf16 v[26:29], v[228:231], v[196:199], v[26:29]
	v_mfma_f32_16x16x32_bf16 v[14:17], v[220:223], v[204:207], v[14:17]
	v_mfma_f32_16x16x32_bf16 v[10:13], v[228:231], v[204:207], v[10:13]
	v_mfma_f32_16x16x32_bf16 v[4:7], v[220:223], v[212:215], v[4:7]
	v_mfma_f32_16x16x32_bf16 v[0:3], v[228:231], v[212:215], v[0:3]
	s_setprio 0
	s_add_i32 s22, 16, 0x18000
	v_add_u32_e32 v153, s22, v154
	s_barrier
	ds_read_b128 v[156:159], v153
	ds_read_b128 v[160:163], v153 offset:1024
	ds_read_b128 v[164:167], v153 offset:2048
	ds_read_b128 v[168:171], v153 offset:3072
	s_add_u32 s20, s70, 0x40000
	s_addc_u32 s21, s71, 0
	s_mov_b32 m0, s11
	v_lshl_add_u64 v[216:217], s[20:21], 0, v[146:147]
	ds_read_b128 v[172:175], v155 offset:32768
	ds_read_b128 v[188:191], v155 offset:33792
	ds_read_b128 v[192:195], v155 offset:34816
	ds_read_b128 v[196:199], v155 offset:35840
	ds_read_b128 v[200:203], v155 offset:36864
	ds_read_b128 v[204:207], v155 offset:37888
	ds_read_b128 v[208:211], v155 offset:38912
	ds_read_b128 v[212:215], v155 offset:39936
	global_load_lds_dwordx4 v[216:217], off
	v_lshl_add_u64 v[216:217], s[20:21], 0, v[142:143]
	s_mov_b32 m0, s12
	s_nop 0
	global_load_lds_dwordx4 v[216:217], off
	s_barrier
	s_waitcnt lgkmcnt(0)
	s_setprio 1
	s_waitcnt lgkmcnt(0)
	v_mfma_f32_16x16x32_bf16 v[126:129], v[156:159], v[172:175], v[126:129]
	v_mfma_f32_16x16x32_bf16 v[122:125], v[164:167], v[172:175], v[122:125]
	v_mfma_f32_16x16x32_bf16 v[118:121], v[156:159], v[192:195], v[118:121]
	v_mfma_f32_16x16x32_bf16 v[110:113], v[164:167], v[192:195], v[110:113]
	v_mfma_f32_16x16x32_bf16 v[102:105], v[156:159], v[200:203], v[102:105]
	v_mfma_f32_16x16x32_bf16 v[94:97], v[164:167], v[200:203], v[94:97]
	v_mfma_f32_16x16x32_bf16 v[86:89], v[156:159], v[208:211], v[86:89]
	v_mfma_f32_16x16x32_bf16 v[78:81], v[164:167], v[208:211], v[78:81]
	v_mfma_f32_16x16x32_bf16 v[126:129], v[160:163], v[188:191], v[126:129]
	v_mfma_f32_16x16x32_bf16 v[122:125], v[168:171], v[188:191], v[122:125]
	v_mfma_f32_16x16x32_bf16 v[118:121], v[160:163], v[196:199], v[118:121]
	v_mfma_f32_16x16x32_bf16 v[110:113], v[168:171], v[196:199], v[110:113]
	v_mfma_f32_16x16x32_bf16 v[102:105], v[160:163], v[204:207], v[102:105]
	v_mfma_f32_16x16x32_bf16 v[94:97], v[168:171], v[204:207], v[94:97]
	v_mfma_f32_16x16x32_bf16 v[86:89], v[160:163], v[212:215], v[86:89]
	v_mfma_f32_16x16x32_bf16 v[78:81], v[168:171], v[212:215], v[78:81]
	s_setprio 0
	s_barrier
	s_add_i32 s23, 16, 0x1c000
	s_add_i32 s20, s22, s8
	v_add_u32_e32 v153, s23, v154
	v_lshl_add_u64 v[232:233], v[232:233], 0, s[94:95]
	s_mov_b32 m0, s20
	ds_read_b128 v[216:219], v153
	ds_read_b128 v[220:223], v153 offset:1024
	ds_read_b128 v[224:227], v153 offset:2048
	ds_read_b128 v[228:231], v153 offset:3072
	global_load_lds_dwordx4 v[232:233], off
	v_lshl_add_u64 v[232:233], v[234:235], 0, s[94:95]
	s_add_i32 m0, s20, 0x2000
	s_nop 0
	global_load_lds_dwordx4 v[232:233], off
	s_barrier
	s_waitcnt lgkmcnt(0)
	s_setprio 1
	s_waitcnt lgkmcnt(0)
	v_mfma_f32_16x16x32_bf16 v[114:117], v[216:219], v[172:175], v[114:117]
	v_mfma_f32_16x16x32_bf16 v[106:109], v[224:227], v[172:175], v[106:109]
	v_mfma_f32_16x16x32_bf16 v[98:101], v[216:219], v[192:195], v[98:101]
	v_mfma_f32_16x16x32_bf16 v[90:93], v[224:227], v[192:195], v[90:93]
	v_mfma_f32_16x16x32_bf16 v[82:85], v[216:219], v[200:203], v[82:85]
	v_mfma_f32_16x16x32_bf16 v[74:77], v[224:227], v[200:203], v[74:77]
	v_mfma_f32_16x16x32_bf16 v[70:73], v[216:219], v[208:211], v[70:73]
	v_mfma_f32_16x16x32_bf16 v[66:69], v[224:227], v[208:211], v[66:69]
	v_mfma_f32_16x16x32_bf16 v[114:117], v[220:223], v[188:191], v[114:117]
	v_mfma_f32_16x16x32_bf16 v[106:109], v[228:231], v[188:191], v[106:109]
	v_mfma_f32_16x16x32_bf16 v[98:101], v[220:223], v[196:199], v[98:101]
	v_mfma_f32_16x16x32_bf16 v[90:93], v[228:231], v[196:199], v[90:93]
	v_mfma_f32_16x16x32_bf16 v[82:85], v[220:223], v[204:207], v[82:85]
	v_mfma_f32_16x16x32_bf16 v[74:77], v[228:231], v[204:207], v[74:77]
	v_mfma_f32_16x16x32_bf16 v[70:73], v[220:223], v[212:215], v[70:73]
	v_mfma_f32_16x16x32_bf16 v[66:69], v[228:231], v[212:215], v[66:69]
	s_setprio 0
	s_mov_b32 m0, s13
	v_lshl_add_u64 v[232:233], v[236:237], 0, s[94:95]
	s_barrier
	ds_read_b128 v[172:175], v155 offset:49152
	ds_read_b128 v[188:191], v155 offset:50176
	ds_read_b128 v[192:195], v155 offset:51200
	ds_read_b128 v[196:199], v155 offset:52224
	ds_read_b128 v[200:203], v155 offset:53248
	ds_read_b128 v[204:207], v155 offset:54272
	ds_read_b128 v[208:211], v155 offset:55296
	ds_read_b128 v[212:215], v155 offset:56320
	global_load_lds_dwordx4 v[232:233], off
	v_lshl_add_u64 v[232:233], v[238:239], 0, s[94:95]
	s_mov_b32 m0, s74
	s_nop 0
	global_load_lds_dwordx4 v[232:233], off
	s_barrier
; #define PG8_STAGE(bufoff, gbase, voff) do { _Pragma("unroll") for (int _i = 0; _i < 2; ++_i) \
;         __builtin_amdgcn_global_load_lds((const unsigned*)((const char*)(gbase) + (voff)[_i]), (LAS unsigned*)(lds + (bufoff) + ldsw + _i * 8192), 16, 0, 0); } while (0)
; #define PG8_MMA(ai, bj, At, Bt) do { __builtin_amdgcn_s_setprio(1); _Pragma("unroll") for (int m = 0; m < 4; ++m) _Pragma("unroll") for (int n = 0; n < 2; ++n) _Pragma("unroll") for (int k = 0; k < 2; ++k) \
;         acc[ai][bj][m][n] = __builtin_amdgcn_mfma_f32_16x16x32_bf16(Bt[n][k], At[m][k], acc[ai][bj][m][n], 0, 0, 0); __builtin_amdgcn_s_setprio(0); } while (0)
; #define PG8_WAIT_V(n) asm volatile("s_waitcnt vmcnt(" #n ")" ::: "memory")
; #define PG8_WAIT_L(n) asm volatile("s_waitcnt lgkmcnt(" #n ")" ::: "memory")
; #define PG8_BAR __builtin_amdgcn_s_barrier()
; #define PG8_SCHED __builtin_amdgcn_sched_barrier(0)
; template <class Epi, class Sched>
; __device__ __forceinline__ void gemm_phase(LAS unsigned char* lds, const Gemm g, const Sched& S, const Epi& E) {
;     ...
;             PG8_BAR; PG8_WAIT_L(0); PG8_MMA(1, 0, At, B0); PG8_BAR; PG8_SCHED;
;             PG8_STAGE(PG8_SB(1, 1), b3 + hstep, voffB);
;             PG8_WAIT_V(6); PG8_BAR; PG8_MMA(1, 1, At, B1); PG8_BAR;
	s_waitcnt lgkmcnt(0)
	s_setprio 1
	s_waitcnt lgkmcnt(0)
	v_mfma_f32_16x16x32_bf16 v[62:65], v[156:159], v[172:175], v[62:65]
	v_mfma_f32_16x16x32_bf16 v[58:61], v[164:167], v[172:175], v[58:61]
	v_mfma_f32_16x16x32_bf16 v[54:57], v[156:159], v[192:195], v[54:57]
	v_mfma_f32_16x16x32_bf16 v[50:53], v[164:167], v[192:195], v[50:53]
	v_mfma_f32_16x16x32_bf16 v[38:41], v[156:159], v[200:203], v[38:41]
	v_mfma_f32_16x16x32_bf16 v[34:37], v[164:167], v[200:203], v[34:37]
	v_mfma_f32_16x16x32_bf16 v[22:25], v[156:159], v[208:211], v[22:25]
	v_mfma_f32_16x16x32_bf16 v[18:21], v[164:167], v[208:211], v[18:21]
	v_mfma_f32_16x16x32_bf16 v[62:65], v[160:163], v[188:191], v[62:65]
	v_mfma_f32_16x16x32_bf16 v[58:61], v[168:171], v[188:191], v[58:61]
	v_mfma_f32_16x16x32_bf16 v[54:57], v[160:163], v[196:199], v[54:57]
	v_mfma_f32_16x16x32_bf16 v[50:53], v[168:171], v[196:199], v[50:53]
	v_mfma_f32_16x16x32_bf16 v[38:41], v[160:163], v[204:207], v[38:41]
	v_mfma_f32_16x16x32_bf16 v[34:37], v[168:171], v[204:207], v[34:37]
	v_mfma_f32_16x16x32_bf16 v[22:25], v[160:163], v[212:215], v[22:25]
	v_mfma_f32_16x16x32_bf16 v[18:21], v[168:171], v[212:215], v[18:21]
	s_setprio 0
	s_barrier
	s_add_u32 s20, s66, 0x40080
	s_addc_u32 s21, s67, 0
	s_add_i32 s22, s23, s8
	v_lshl_add_u64 v[156:157], s[20:21], 0, v[144:145]
	s_mov_b32 m0, s22
	s_nop 0
	global_load_lds_dwordx4 v[156:157], off
	v_lshl_add_u64 v[156:157], s[20:21], 0, v[140:141]
	s_add_i32 m0, s22, 0x2000
	s_nop 0
	global_load_lds_dwordx4 v[156:157], off
	s_waitcnt vmcnt(6)
	s_barrier
	s_setprio 1
	v_mfma_f32_16x16x32_bf16 v[46:49], v[216:219], v[172:175], v[46:49]
	v_mfma_f32_16x16x32_bf16 v[42:45], v[224:227], v[172:175], v[42:45]
	v_mfma_f32_16x16x32_bf16 v[30:33], v[216:219], v[192:195], v[30:33]
	v_mfma_f32_16x16x32_bf16 v[26:29], v[224:227], v[192:195], v[26:29]
	v_mfma_f32_16x16x32_bf16 v[14:17], v[216:219], v[200:203], v[14:17]
	v_mfma_f32_16x16x32_bf16 v[10:13], v[224:227], v[200:203], v[10:13]
	v_mfma_f32_16x16x32_bf16 v[4:7], v[216:219], v[208:211], v[4:7]
	v_mfma_f32_16x16x32_bf16 v[0:3], v[224:227], v[208:211], v[0:3]
	v_mfma_f32_16x16x32_bf16 v[46:49], v[220:223], v[188:191], v[46:49]
	v_mfma_f32_16x16x32_bf16 v[42:45], v[228:231], v[188:191], v[42:45]
	v_mfma_f32_16x16x32_bf16 v[30:33], v[220:223], v[196:199], v[30:33]
	v_mfma_f32_16x16x32_bf16 v[26:29], v[228:231], v[196:199], v[26:29]
	v_mfma_f32_16x16x32_bf16 v[14:17], v[220:223], v[204:207], v[14:17]
	v_mfma_f32_16x16x32_bf16 v[10:13], v[228:231], v[204:207], v[10:13]
	v_mfma_f32_16x16x32_bf16 v[4:7], v[220:223], v[212:215], v[4:7]
	v_mfma_f32_16x16x32_bf16 v[0:3], v[228:231], v[212:215], v[0:3]
	s_setprio 0
	s_add_i32 s19, s19, 2
	s_add_u32 s72, s72, 0x100
	s_addc_u32 s73, s73, 0
	s_add_u32 s17, s17, 0x100
	s_addc_u32 s18, s18, 0
	s_cmp_gt_u32 s19, 13
	s_barrier
	s_cbranch_scc0 .LBB0_187
; __device__ __forceinline__ unsigned pk_bf16(float a, float b) { f32x2 v = {a, b}; bf2_t r = __builtin_convertvector(v, bf2_t); return __builtin_bit_cast(unsigned, r); }
; #define PG8_WAIT_V(n) asm volatile("s_waitcnt vmcnt(" #n ")" ::: "memory")
; #define PG8_BAR __builtin_amdgcn_s_barrier()
;     __device__ __forceinline__ void operator()(const f32x4 (&acc)[2][2][4][2], const Unit& u, int wr, int wc, int fr, int fq) const {
;         const int row0 = u.pm * BM + wr * 64 + fr; int colt = u.pn * BM; bf16_t* base = O;
;         if (split_cols) { const int t = colt / split_cols; base += (size_t)t * split_stride; colt -= t * split_cols; }
;         const int col0 = colt + wc * 32 + 8 * fq;
; #pragma unroll
;         for (int ai = 0; ai < 2; ++ai)
; #pragma unroll
;             for (int m = 0; m < 4; ++m) { const int row = row0 + ai * HALF + m * 16;
;                 bf16_t* rowp = slot_stride ? base + (size_t)(colt >> 7) * slot_stride + (size_t)row * 128 + wc * 32 + 8 * fq : base + (size_t)row * ldc + col0;
; #pragma unroll
;                 for (int bj = 0; bj < 2; ++bj) { const f32x4 v0 = acc[ai][bj][m][0], v1 = acc[ai][bj][m][1];
;                     u32x4 w; w.x = pk_bf16(v0[0], v0[1]); w.y = pk_bf16(v0[2], v0[3]); w.z = pk_bf16(v1[0], v1[1]); w.w = pk_bf16(v1[2], v1[3]);
;                     *(u32x4*)(rowp + (slot_stride ? (size_t)bj * slot_stride : (size_t)bj * HALF)) = w; } }
; template <class Epi, class Sched>
; __device__ __forceinline__ void gemm_phase(LAS unsigned char* lds, const Gemm g, const Sched& S, const Epi& E) {
;     ...
;         E(acc, cur, wr, wc, fr, fq); S.done(cur);
;         if (!has_next) break;
; #pragma unroll
;         for (int a = 0; a < 2; ++a)
; #pragma unroll
;             for (int b = 0; b < 2; ++b)
; #pragma unroll
;                 for (int m = 0; m < 4; ++m)
; #pragma unroll
;                     for (int n = 0; n < 2; ++n) acc[a][b][m][n] = (f32x4){0.f, 0.f, 0.f, 0.f};
;         cur = nxt; cA = nA; cB = nB; ++ui;
;     }
;     PG8_WAIT_V(0);
;     if (wr == 0) PG8_BAR;
;     PG8_BAR;
	v_lshl_add_u32 v156, s75, 8, v9
	s_lshl_b32 s1, s15, 1
	s_mul_i32 s15, s15, 0x1100000
	s_mul_hi_i32 s1, s1, 0x880000
	s_add_u32 s66, s82, s15
	v_ashrrev_i32_e32 v157, 31, v156
	s_addc_u32 s67, s83, s1
	v_lshlrev_b64 v[158:159], 8, v[156:157]
	v_lshl_add_u64 v[158:159], s[66:67], 0, v[158:159]
	v_lshl_add_u64 v[158:159], v[158:159], 0, s[2:3]
	v_mov_b32_e32 v153, v8
	v_lshl_add_u64 v[158:159], v[158:159], 0, v[152:153]
	v_cvt_pk_bf16_f32 v114, v114, v115
	v_cvt_pk_bf16_f32 v115, v116, v117
	v_cvt_pk_bf16_f32 v116, v106, v107
	v_add_co_u32_e32 v106, vcc, s87, v158
	v_cvt_pk_bf16_f32 v117, v108, v109
	s_nop 0
	v_addc_co_u32_e32 v107, vcc, 0, v159, vcc
	global_store_dwordx4 v[106:107], v[114:117], off
	v_or_b32_e32 v106, 16, v156
	v_ashrrev_i32_e32 v107, 31, v106
	v_lshlrev_b64 v[106:107], 8, v[106:107]
	v_lshl_add_u64 v[106:107], s[66:67], 0, v[106:107]
	v_lshl_add_u64 v[106:107], v[106:107], 0, s[2:3]
	v_lshl_add_u64 v[114:115], v[106:107], 0, v[152:153]
	v_cvt_pk_bf16_f32 v98, v98, v99
	v_cvt_pk_bf16_f32 v99, v100, v101
	v_cvt_pk_bf16_f32 v100, v90, v91
	v_add_co_u32_e32 v90, vcc, s87, v114
	v_cvt_pk_bf16_f32 v101, v92, v93
	s_nop 0
	v_addc_co_u32_e32 v91, vcc, 0, v115, vcc
	global_store_dwordx4 v[90:91], v[98:101], off
	v_or_b32_e32 v90, 32, v156
	v_ashrrev_i32_e32 v91, 31, v90
	v_lshlrev_b64 v[90:91], 8, v[90:91]
	v_lshl_add_u64 v[90:91], s[66:67], 0, v[90:91]
	v_lshl_add_u64 v[90:91], v[90:91], 0, s[2:3]
	v_lshl_add_u64 v[98:99], v[90:91], 0, v[152:153]
	v_cvt_pk_bf16_f32 v82, v82, v83
	v_cvt_pk_bf16_f32 v83, v84, v85
	v_cvt_pk_bf16_f32 v84, v74, v75
	v_add_co_u32_e32 v74, vcc, s87, v98
	v_cvt_pk_bf16_f32 v85, v76, v77
	s_nop 0
	v_addc_co_u32_e32 v75, vcc, 0, v99, vcc
	global_store_dwordx4 v[74:75], v[82:85], off
	v_or_b32_e32 v74, 48, v156
	v_ashrrev_i32_e32 v75, 31, v74
	v_lshlrev_b64 v[74:75], 8, v[74:75]
	v_lshl_add_u64 v[74:75], s[66:67], 0, v[74:75]
	v_lshl_add_u64 v[74:75], v[74:75], 0, s[2:3]
	v_lshl_add_u64 v[82:83], v[74:75], 0, v[152:153]
	v_cvt_pk_bf16_f32 v70, v70, v71
	v_cvt_pk_bf16_f32 v71, v72, v73
	v_cvt_pk_bf16_f32 v72, v66, v67
	v_add_co_u32_e32 v66, vcc, s87, v82
	s_mov_b32 s1, 0x9000
	s_nop 0
	v_addc_co_u32_e32 v67, vcc, 0, v83, vcc
	v_cvt_pk_bf16_f32 v62, v62, v63
	v_cvt_pk_bf16_f32 v63, v64, v65
	v_cvt_pk_bf16_f32 v64, v58, v59
	v_add_co_u32_e32 v58, vcc, s1, v158
	s_mov_b32 s1, 0x889000
	s_nop 0
	v_addc_co_u32_e32 v59, vcc, 0, v159, vcc
	v_cvt_pk_bf16_f32 v65, v60, v61
	v_add_co_u32_e32 v60, vcc, s1, v158
	v_cvt_pk_bf16_f32 v30, v30, v31
	s_nop 0
	v_addc_co_u32_e32 v61, vcc, 0, v159, vcc
	v_cvt_pk_bf16_f32 v31, v32, v33
	v_cvt_pk_bf16_f32 v32, v26, v27
	v_cvt_pk_bf16_f32 v33, v28, v29
	s_mov_b32 s1, 0xb000
	global_store_dwordx4 v[60:61], v[30:33], off
	v_cvt_pk_bf16_f32 v14, v14, v15
	v_cvt_pk_bf16_f32 v15, v16, v17
	v_add_co_u32_e32 v30, vcc, s1, v158
	s_mov_b32 s1, 0x88a000
	s_nop 0
	v_addc_co_u32_e32 v31, vcc, 0, v159, vcc
	v_cvt_pk_bf16_f32 v16, v10, v11
	v_add_co_u32_e32 v10, vcc, s1, v158
	v_cvt_pk_bf16_f32 v4, v4, v5
	s_nop 0
	v_addc_co_u32_e32 v11, vcc, 0, v159, vcc
	v_cvt_pk_bf16_f32 v5, v6, v7
	v_cvt_pk_bf16_f32 v6, v0, v1
	v_add_co_u32_e32 v0, vcc, 0x88b000, v158
	v_cvt_pk_bf16_f32 v17, v12, v13
	s_nop 0
	v_addc_co_u32_e32 v1, vcc, 0, v159, vcc
	v_cvt_pk_bf16_f32 v126, v126, v127
	v_cvt_pk_bf16_f32 v127, v128, v129
	v_cvt_pk_bf16_f32 v128, v122, v123
	v_cvt_pk_bf16_f32 v129, v124, v125
	v_cvt_pk_bf16_f32 v106, v118, v119
	v_cvt_pk_bf16_f32 v107, v120, v121
	v_cvt_pk_bf16_f32 v108, v110, v111
	v_cvt_pk_bf16_f32 v109, v112, v113
	v_cvt_pk_bf16_f32 v90, v102, v103
	v_cvt_pk_bf16_f32 v91, v104, v105
	v_cvt_pk_bf16_f32 v92, v94, v95
	v_cvt_pk_bf16_f32 v93, v96, v97
	v_cvt_pk_bf16_f32 v74, v86, v87
	v_cvt_pk_bf16_f32 v75, v88, v89
	v_cvt_pk_bf16_f32 v76, v78, v79
	v_cvt_pk_bf16_f32 v77, v80, v81
	v_cvt_pk_bf16_f32 v73, v68, v69
	v_cvt_pk_bf16_f32 v46, v46, v47
	v_cvt_pk_bf16_f32 v47, v48, v49
	v_cvt_pk_bf16_f32 v48, v42, v43
	v_cvt_pk_bf16_f32 v49, v44, v45
	v_cvt_pk_bf16_f32 v42, v54, v55
	v_cvt_pk_bf16_f32 v43, v56, v57
	v_cvt_pk_bf16_f32 v44, v50, v51
	v_cvt_pk_bf16_f32 v45, v52, v53
	v_cvt_pk_bf16_f32 v26, v38, v39
	v_cvt_pk_bf16_f32 v27, v40, v41
	v_cvt_pk_bf16_f32 v28, v34, v35
	v_cvt_pk_bf16_f32 v29, v36, v37
	global_store_dwordx4 v[10:11], v[14:17], off
	v_cvt_pk_bf16_f32 v10, v22, v23
	v_cvt_pk_bf16_f32 v11, v24, v25
	v_cvt_pk_bf16_f32 v12, v18, v19
	v_cvt_pk_bf16_f32 v13, v20, v21
	v_cvt_pk_bf16_f32 v7, v2, v3
	s_and_b64 vcc, exec, s[38:39]
	s_mov_b32 s15, s0
	s_mov_b32 s75, s40
	s_mov_b64 s[66:67], s[88:89]
	s_mov_b64 s[70:71], s[42:43]
	global_store_dwordx4 v[158:159], v[126:129], off
	global_store_dwordx4 v[114:115], v[106:109], off
	global_store_dwordx4 v[98:99], v[90:93], off
	global_store_dwordx4 v[82:83], v[74:77], off
	global_store_dwordx4 v[66:67], v[70:73], off
	global_store_dwordx4 v[58:59], v[62:65], off offset:-4096
	global_store_dwordx4 v[60:61], v[46:49], off offset:-4096
	global_store_dwordx4 v[58:59], v[42:45], off
	global_store_dwordx4 v[30:31], v[26:29], off offset:-4096
	global_store_dwordx4 v[30:31], v[10:13], off
	global_store_dwordx4 v[0:1], v[4:7], off
	s_cbranch_vccz .LBB0_184
	s_waitcnt vmcnt(0)
	v_readlane_b32 s14, v244, 49
	v_readlane_b32 s16, v244, 51
	v_readlane_b32 s70, v244, 55
	s_cmpk_gt_u32 s5, 0xff
	v_readlane_b32 s15, v244, 50
	v_readlane_b32 s17, v244, 52
	v_readlane_b32 s71, v244, 56
	s_cbranch_scc1 .LBB0_191
	s_barrier

; #define PG8_STAGE(bufoff, gbase, voff) do { _Pragma("unroll") for (int _i = 0; _i < 2; ++_i) \
;         __builtin_amdgcn_global_load_lds((const unsigned*)((const char*)(gbase) + (voff)[_i]), (LAS unsigned*)(lds + (bufoff) + ldsw + _i * 8192), 16, 0, 0); } while (0)
; #define PG8_LDA(dst, b, h) do { _Pragma("unroll") for (int m = 0; m < 4; ++m) _Pragma("unroll") for (int k = 0; k < 2; ++k) dst[m][k] = *(const LAS bf16x8*)(lds + PG8_SA(b, h) + aoff + m * 2048 + k * 1024); } while (0)
; #define PG8_LDB(dst, b, h) do { _Pragma("unroll") for (int n = 0; n < 2; ++n) _Pragma("unroll") for (int k = 0; k < 2; ++k) dst[n][k] = *(const LAS bf16x8*)(lds + PG8_SB(b, h) + boff + n * 2048 + k * 1024); } while (0)
; #define PG8_MMA(ai, bj, At, Bt) do { __builtin_amdgcn_s_setprio(1); _Pragma("unroll") for (int m = 0; m < 4; ++m) _Pragma("unroll") for (int n = 0; n < 2; ++n) _Pragma("unroll") for (int k = 0; k < 2; ++k) \
;         acc[ai][bj][m][n] = __builtin_amdgcn_mfma_f32_16x16x32_bf16(Bt[n][k], At[m][k], acc[ai][bj][m][n], 0, 0, 0); __builtin_amdgcn_s_setprio(0); } while (0)
; #define PG8_WAIT_L(n) asm volatile("s_waitcnt lgkmcnt(" #n ")" ::: "memory")
; #define PG8_BAR __builtin_amdgcn_s_barrier()
; #define PG8_SCHED __builtin_amdgcn_sched_barrier(0)
; template <class Epi, class Sched>
; __device__ __forceinline__ void gemm_phase(LAS unsigned char* lds, const Gemm g, const Sched& S, const Epi& E) {
;     ...
;         for (int t = 0; t < nt; t += 2) {
;             const bool last = (t == nt - 2);
;             const char* a1 = cA + (size_t)(t + 1) * kstep;
;             const char* a2 = last ? nA : cA + (size_t)(t + 2) * kstep; const char* b2 = last ? nB : cB + (size_t)(t + 2) * kstep;
;             const char* a3 = a2 + kstep; const char* b3 = b2 + kstep;
;             if (last && has_next) S.a_ready(nxt);
;             PG8_LDB(B0, 0, 0); PG8_SCHED; PG8_LDA(At, 0, 0); PG8_STAGE(PG8_SA(1, 1), a1 + hstep, voffA);
;             PG8_WAIT_L(8); PG8_BAR; PG8_WAIT_L(0); PG8_MMA(0, 0, At, B0); PG8_BAR; PG8_SCHED;
;             PG8_LDB(B1, 0, 1); PG8_STAGE(PG8_SB(0, 0), b2, voffB);
;             PG8_BAR; PG8_WAIT_L(0); PG8_MMA(0, 1, At, B1); PG8_BAR;
;             PG8_LDA(At, 0, 1); PG8_STAGE(PG8_SA(0, 0), a2, voffA);
;             PG8_BAR; PG8_WAIT_L(0); PG8_MMA(1, 0, At, B0); PG8_BAR; PG8_SCHED;
.LBB0_515:
	s_add_u32 s20, vcc_lo, 0xfffc0080
	s_addc_u32 s21, vcc_hi, -1
	s_add_i32 s22, 16, 0x10000
	v_add_u32_e32 v155, s22, v152
	ds_read_b128 v[156:159], v155
	ds_read_b128 v[160:163], v155 offset:1024
	ds_read_b128 v[164:167], v155 offset:2048
	ds_read_b128 v[168:171], v155 offset:3072
	s_cmp_eq_u32 s19, 12
	s_cselect_b32 s73, s89, s21
	s_cselect_b32 s72, s16, s20
	s_cselect_b32 s67, s17, s18
	s_cselect_b32 s66, s43, s74
	v_lshl_add_u64 v[216:217], vcc, 0, v[148:149]
	s_add_i32 m0, s1, 0xc000
	ds_read_b128 v[172:175], v154
	ds_read_b128 v[188:191], v154 offset:1024
	ds_read_b128 v[192:195], v154 offset:2048
	ds_read_b128 v[196:199], v154 offset:3072
	ds_read_b128 v[200:203], v154 offset:4096
	ds_read_b128 v[204:207], v154 offset:5120
	ds_read_b128 v[208:211], v154 offset:6144
	ds_read_b128 v[212:215], v154 offset:7168
	global_load_lds_dwordx4 v[216:217], off
	v_lshl_add_u64 v[216:217], vcc, 0, v[150:151]
	s_add_i32 m0, s1, 0xe000
	s_nop 0
	global_load_lds_dwordx4 v[216:217], off
	s_barrier
	s_waitcnt lgkmcnt(0)
	s_setprio 1
	s_waitcnt lgkmcnt(0)
	v_mfma_f32_16x16x32_bf16 v[126:129], v[156:159], v[172:175], v[126:129]
	v_mfma_f32_16x16x32_bf16 v[122:125], v[164:167], v[172:175], v[122:125]
	v_mfma_f32_16x16x32_bf16 v[118:121], v[156:159], v[192:195], v[118:121]
	v_mfma_f32_16x16x32_bf16 v[114:117], v[164:167], v[192:195], v[114:117]
	v_mfma_f32_16x16x32_bf16 v[102:105], v[156:159], v[200:203], v[102:105]
	v_mfma_f32_16x16x32_bf16 v[98:101], v[164:167], v[200:203], v[98:101]
	v_mfma_f32_16x16x32_bf16 v[86:89], v[156:159], v[208:211], v[86:89]
	v_mfma_f32_16x16x32_bf16 v[82:85], v[164:167], v[208:211], v[82:85]
	v_mfma_f32_16x16x32_bf16 v[126:129], v[160:163], v[188:191], v[126:129]
	v_mfma_f32_16x16x32_bf16 v[122:125], v[168:171], v[188:191], v[122:125]
	v_mfma_f32_16x16x32_bf16 v[118:121], v[160:163], v[196:199], v[118:121]
	v_mfma_f32_16x16x32_bf16 v[114:117], v[168:171], v[196:199], v[114:117]
	v_mfma_f32_16x16x32_bf16 v[102:105], v[160:163], v[204:207], v[102:105]
	v_mfma_f32_16x16x32_bf16 v[98:101], v[168:171], v[204:207], v[98:101]
	v_mfma_f32_16x16x32_bf16 v[86:89], v[160:163], v[212:215], v[86:89]
	v_mfma_f32_16x16x32_bf16 v[82:85], v[168:171], v[212:215], v[82:85]
	s_setprio 0
	s_barrier
	s_add_i32 s23, 16, 0x14000
	s_add_i32 s20, s22, s9
	v_add_u32_e32 v155, s23, v152
	v_lshl_add_u64 v[232:233], s[66:67], 0, v[144:145]
	s_mov_b32 m0, s20
	ds_read_b128 v[216:219], v155
	ds_read_b128 v[220:223], v155 offset:1024
	ds_read_b128 v[224:227], v155 offset:2048
	ds_read_b128 v[228:231], v155 offset:3072
	global_load_lds_dwordx4 v[232:233], off
	v_lshl_add_u64 v[234:235], s[66:67], 0, v[140:141]
	s_add_i32 m0, s20, 0x2000
	s_nop 0
	global_load_lds_dwordx4 v[234:235], off
	s_barrier
	s_waitcnt lgkmcnt(0)
	s_setprio 1
	s_waitcnt lgkmcnt(0)
	v_mfma_f32_16x16x32_bf16 v[110:113], v[216:219], v[172:175], v[110:113]
	v_mfma_f32_16x16x32_bf16 v[106:109], v[224:227], v[172:175], v[106:109]
	v_mfma_f32_16x16x32_bf16 v[94:97], v[216:219], v[192:195], v[94:97]
	v_mfma_f32_16x16x32_bf16 v[90:93], v[224:227], v[192:195], v[90:93]
	v_mfma_f32_16x16x32_bf16 v[78:81], v[216:219], v[200:203], v[78:81]
	v_mfma_f32_16x16x32_bf16 v[74:77], v[224:227], v[200:203], v[74:77]
	v_mfma_f32_16x16x32_bf16 v[70:73], v[216:219], v[208:211], v[70:73]
	v_mfma_f32_16x16x32_bf16 v[66:69], v[224:227], v[208:211], v[66:69]
	v_mfma_f32_16x16x32_bf16 v[110:113], v[220:223], v[188:191], v[110:113]
	v_mfma_f32_16x16x32_bf16 v[106:109], v[228:231], v[188:191], v[106:109]
	v_mfma_f32_16x16x32_bf16 v[94:97], v[220:223], v[196:199], v[94:97]
	v_mfma_f32_16x16x32_bf16 v[90:93], v[228:231], v[196:199], v[90:93]
	v_mfma_f32_16x16x32_bf16 v[78:81], v[220:223], v[204:207], v[78:81]
	v_mfma_f32_16x16x32_bf16 v[74:77], v[228:231], v[204:207], v[74:77]
	v_mfma_f32_16x16x32_bf16 v[70:73], v[220:223], v[212:215], v[70:73]
	v_mfma_f32_16x16x32_bf16 v[66:69], v[228:231], v[212:215], v[66:69]
	s_setprio 0
	s_mov_b32 m0, s1
	v_lshl_add_u64 v[236:237], s[72:73], 0, v[146:147]
	s_barrier
	ds_read_b128 v[172:175], v154 offset:16384
	ds_read_b128 v[188:191], v154 offset:17408
	ds_read_b128 v[192:195], v154 offset:18432
	ds_read_b128 v[196:199], v154 offset:19456
	ds_read_b128 v[200:203], v154 offset:20480
	ds_read_b128 v[204:207], v154 offset:21504
	ds_read_b128 v[208:211], v154 offset:22528
	ds_read_b128 v[212:215], v154 offset:23552
	global_load_lds_dwordx4 v[236:237], off
	v_lshl_add_u64 v[238:239], s[72:73], 0, v[142:143]
	s_mov_b32 m0, s11
	s_nop 0
	global_load_lds_dwordx4 v[238:239], off
	s_barrier
	s_waitcnt lgkmcnt(0)
	s_setprio 1
	s_waitcnt lgkmcnt(0)
	v_mfma_f32_16x16x32_bf16 v[62:65], v[156:159], v[172:175], v[62:65]
	v_mfma_f32_16x16x32_bf16 v[58:61], v[164:167], v[172:175], v[58:61]
	v_mfma_f32_16x16x32_bf16 v[54:57], v[156:159], v[192:195], v[54:57]
	v_mfma_f32_16x16x32_bf16 v[50:53], v[164:167], v[192:195], v[50:53]
	v_mfma_f32_16x16x32_bf16 v[38:41], v[156:159], v[200:203], v[38:41]
	v_mfma_f32_16x16x32_bf16 v[34:37], v[164:167], v[200:203], v[34:37]
	v_mfma_f32_16x16x32_bf16 v[22:25], v[156:159], v[208:211], v[22:25]
	v_mfma_f32_16x16x32_bf16 v[18:21], v[164:167], v[208:211], v[18:21]
	v_mfma_f32_16x16x32_bf16 v[62:65], v[160:163], v[188:191], v[62:65]
	v_mfma_f32_16x16x32_bf16 v[58:61], v[168:171], v[188:191], v[58:61]
	v_mfma_f32_16x16x32_bf16 v[54:57], v[160:163], v[196:199], v[54:57]
	v_mfma_f32_16x16x32_bf16 v[50:53], v[168:171], v[196:199], v[50:53]
	v_mfma_f32_16x16x32_bf16 v[38:41], v[160:163], v[204:207], v[38:41]
	v_mfma_f32_16x16x32_bf16 v[34:37], v[168:171], v[204:207], v[34:37]
	v_mfma_f32_16x16x32_bf16 v[22:25], v[160:163], v[212:215], v[22:25]
	v_mfma_f32_16x16x32_bf16 v[18:21], v[168:171], v[212:215], v[18:21]
	s_setprio 0
	s_barrier
; #define PG8_STAGE(bufoff, gbase, voff) do { _Pragma("unroll") for (int _i = 0; _i < 2; ++_i) \
;         __builtin_amdgcn_global_load_lds((const unsigned*)((const char*)(gbase) + (voff)[_i]), (LAS unsigned*)(lds + (bufoff) + ldsw + _i * 8192), 16, 0, 0); } while (0)
; #define PG8_LDA(dst, b, h) do { _Pragma("unroll") for (int m = 0; m < 4; ++m) _Pragma("unroll") for (int k = 0; k < 2; ++k) dst[m][k] = *(const LAS bf16x8*)(lds + PG8_SA(b, h) + aoff + m * 2048 + k * 1024); } while (0)
; #define PG8_LDB(dst, b, h) do { _Pragma("unroll") for (int n = 0; n < 2; ++n) _Pragma("unroll") for (int k = 0; k < 2; ++k) dst[n][k] = *(const LAS bf16x8*)(lds + PG8_SB(b, h) + boff + n * 2048 + k * 1024); } while (0)
; #define PG8_MMA(ai, bj, At, Bt) do { __builtin_amdgcn_s_setprio(1); _Pragma("unroll") for (int m = 0; m < 4; ++m) _Pragma("unroll") for (int n = 0; n < 2; ++n) _Pragma("unroll") for (int k = 0; k < 2; ++k) \
;         acc[ai][bj][m][n] = __builtin_amdgcn_mfma_f32_16x16x32_bf16(Bt[n][k], At[m][k], acc[ai][bj][m][n], 0, 0, 0); __builtin_amdgcn_s_setprio(0); } while (0)
; #define PG8_WAIT_V(n) asm volatile("s_waitcnt vmcnt(" #n ")" ::: "memory")
; #define PG8_WAIT_L(n) asm volatile("s_waitcnt lgkmcnt(" #n ")" ::: "memory")
; #define PG8_BAR __builtin_amdgcn_s_barrier()
; #define PG8_SCHED __builtin_amdgcn_sched_barrier(0)
; template <class Epi, class Sched>
; __device__ __forceinline__ void gemm_phase(LAS unsigned char* lds, const Gemm g, const Sched& S, const Epi& E) {
;     ...
;             PG8_STAGE(PG8_SB(0, 1), b2 + hstep, voffB);
;             PG8_WAIT_V(6); PG8_BAR; PG8_MMA(1, 1, At, B1); PG8_BAR;
;             PG8_LDB(B0, 1, 0); PG8_SCHED; PG8_LDA(At, 1, 0); PG8_STAGE(PG8_SA(0, 1), a2 + hstep, voffA);
;             PG8_WAIT_L(8); PG8_BAR; PG8_WAIT_L(0); PG8_MMA(0, 0, At, B0); PG8_BAR; PG8_SCHED;
;             PG8_LDB(B1, 1, 1); PG8_STAGE(PG8_SB(1, 0), b3, voffB);
;             PG8_BAR; PG8_WAIT_L(0); PG8_MMA(0, 1, At, B1); PG8_BAR;
;             PG8_LDA(At, 1, 1); PG8_STAGE(PG8_SA(1, 0), a3, voffA);
	s_add_u32 s20, s66, 0x40000
	s_addc_u32 s21, s67, 0
	s_add_i32 s22, s23, s9
	v_lshl_add_u64 v[156:157], s[20:21], 0, v[144:145]
	s_mov_b32 m0, s22
	s_nop 0
	global_load_lds_dwordx4 v[156:157], off
	v_lshl_add_u64 v[156:157], s[20:21], 0, v[140:141]
	s_add_i32 m0, s22, 0x2000
	s_nop 0
	global_load_lds_dwordx4 v[156:157], off
	s_waitcnt vmcnt(6)
	s_barrier
	s_setprio 1
	v_mfma_f32_16x16x32_bf16 v[46:49], v[216:219], v[172:175], v[46:49]
	v_mfma_f32_16x16x32_bf16 v[42:45], v[224:227], v[172:175], v[42:45]
	v_mfma_f32_16x16x32_bf16 v[30:33], v[216:219], v[192:195], v[30:33]
	v_mfma_f32_16x16x32_bf16 v[26:29], v[224:227], v[192:195], v[26:29]
	v_mfma_f32_16x16x32_bf16 v[14:17], v[216:219], v[200:203], v[14:17]
	v_mfma_f32_16x16x32_bf16 v[10:13], v[224:227], v[200:203], v[10:13]
	v_mfma_f32_16x16x32_bf16 v[4:7], v[216:219], v[208:211], v[4:7]
	v_mfma_f32_16x16x32_bf16 v[0:3], v[224:227], v[208:211], v[0:3]
	v_mfma_f32_16x16x32_bf16 v[46:49], v[220:223], v[188:191], v[46:49]
	v_mfma_f32_16x16x32_bf16 v[42:45], v[228:231], v[188:191], v[42:45]
	v_mfma_f32_16x16x32_bf16 v[30:33], v[220:223], v[196:199], v[30:33]
	v_mfma_f32_16x16x32_bf16 v[26:29], v[228:231], v[196:199], v[26:29]
	v_mfma_f32_16x16x32_bf16 v[14:17], v[220:223], v[204:207], v[14:17]
	v_mfma_f32_16x16x32_bf16 v[10:13], v[228:231], v[204:207], v[10:13]
	v_mfma_f32_16x16x32_bf16 v[4:7], v[220:223], v[212:215], v[4:7]
	v_mfma_f32_16x16x32_bf16 v[0:3], v[228:231], v[212:215], v[0:3]
	s_setprio 0
	s_add_i32 s22, 16, 0x18000
	v_add_u32_e32 v155, s22, v152
	s_barrier
	ds_read_b128 v[156:159], v155
	ds_read_b128 v[160:163], v155 offset:1024
	ds_read_b128 v[164:167], v155 offset:2048
	ds_read_b128 v[168:171], v155 offset:3072
	s_add_u32 s20, s72, 0x40000
	s_addc_u32 s21, s73, 0
	s_mov_b32 m0, s41
	v_lshl_add_u64 v[216:217], s[20:21], 0, v[146:147]
	ds_read_b128 v[172:175], v154 offset:32768
	ds_read_b128 v[188:191], v154 offset:33792
	ds_read_b128 v[192:195], v154 offset:34816
	ds_read_b128 v[196:199], v154 offset:35840
	ds_read_b128 v[200:203], v154 offset:36864
	ds_read_b128 v[204:207], v154 offset:37888
	ds_read_b128 v[208:211], v154 offset:38912
	ds_read_b128 v[212:215], v154 offset:39936
	global_load_lds_dwordx4 v[216:217], off
	v_lshl_add_u64 v[216:217], s[20:21], 0, v[142:143]
	s_mov_b32 m0, s12
	s_nop 0
	global_load_lds_dwordx4 v[216:217], off
	s_barrier
	s_waitcnt lgkmcnt(0)
	s_setprio 1
	s_waitcnt lgkmcnt(0)
	v_mfma_f32_16x16x32_bf16 v[126:129], v[156:159], v[172:175], v[126:129]
	v_mfma_f32_16x16x32_bf16 v[122:125], v[164:167], v[172:175], v[122:125]
	v_mfma_f32_16x16x32_bf16 v[118:121], v[156:159], v[192:195], v[118:121]
	v_mfma_f32_16x16x32_bf16 v[114:117], v[164:167], v[192:195], v[114:117]
	v_mfma_f32_16x16x32_bf16 v[102:105], v[156:159], v[200:203], v[102:105]
	v_mfma_f32_16x16x32_bf16 v[98:101], v[164:167], v[200:203], v[98:101]
	v_mfma_f32_16x16x32_bf16 v[86:89], v[156:159], v[208:211], v[86:89]
	v_mfma_f32_16x16x32_bf16 v[82:85], v[164:167], v[208:211], v[82:85]
	v_mfma_f32_16x16x32_bf16 v[126:129], v[160:163], v[188:191], v[126:129]
	v_mfma_f32_16x16x32_bf16 v[122:125], v[168:171], v[188:191], v[122:125]
	v_mfma_f32_16x16x32_bf16 v[118:121], v[160:163], v[196:199], v[118:121]
	v_mfma_f32_16x16x32_bf16 v[114:117], v[168:171], v[196:199], v[114:117]
	v_mfma_f32_16x16x32_bf16 v[102:105], v[160:163], v[204:207], v[102:105]
	v_mfma_f32_16x16x32_bf16 v[98:101], v[168:171], v[204:207], v[98:101]
	v_mfma_f32_16x16x32_bf16 v[86:89], v[160:163], v[212:215], v[86:89]
	v_mfma_f32_16x16x32_bf16 v[82:85], v[168:171], v[212:215], v[82:85]
	s_setprio 0
	s_barrier
	s_add_i32 s23, 16, 0x1c000
	s_add_i32 s20, s22, s9
	v_add_u32_e32 v155, s23, v152
	v_lshl_add_u64 v[232:233], v[232:233], 0, s[94:95]
	s_mov_b32 m0, s20
	ds_read_b128 v[216:219], v155
	ds_read_b128 v[220:223], v155 offset:1024
	ds_read_b128 v[224:227], v155 offset:2048
	ds_read_b128 v[228:231], v155 offset:3072
	global_load_lds_dwordx4 v[232:233], off
	v_lshl_add_u64 v[232:233], v[234:235], 0, s[94:95]
	s_add_i32 m0, s20, 0x2000
	s_nop 0
	global_load_lds_dwordx4 v[232:233], off
	s_barrier
	s_waitcnt lgkmcnt(0)
	s_setprio 1
	s_waitcnt lgkmcnt(0)
	v_mfma_f32_16x16x32_bf16 v[110:113], v[216:219], v[172:175], v[110:113]
	v_mfma_f32_16x16x32_bf16 v[106:109], v[224:227], v[172:175], v[106:109]
	v_mfma_f32_16x16x32_bf16 v[94:97], v[216:219], v[192:195], v[94:97]
	v_mfma_f32_16x16x32_bf16 v[90:93], v[224:227], v[192:195], v[90:93]
	v_mfma_f32_16x16x32_bf16 v[78:81], v[216:219], v[200:203], v[78:81]
	v_mfma_f32_16x16x32_bf16 v[74:77], v[224:227], v[200:203], v[74:77]
	v_mfma_f32_16x16x32_bf16 v[70:73], v[216:219], v[208:211], v[70:73]
	v_mfma_f32_16x16x32_bf16 v[66:69], v[224:227], v[208:211], v[66:69]
	v_mfma_f32_16x16x32_bf16 v[110:113], v[220:223], v[188:191], v[110:113]
	v_mfma_f32_16x16x32_bf16 v[106:109], v[228:231], v[188:191], v[106:109]
	v_mfma_f32_16x16x32_bf16 v[94:97], v[220:223], v[196:199], v[94:97]
	v_mfma_f32_16x16x32_bf16 v[90:93], v[228:231], v[196:199], v[90:93]
	v_mfma_f32_16x16x32_bf16 v[78:81], v[220:223], v[204:207], v[78:81]
	v_mfma_f32_16x16x32_bf16 v[74:77], v[228:231], v[204:207], v[74:77]
	v_mfma_f32_16x16x32_bf16 v[70:73], v[220:223], v[212:215], v[70:73]
	v_mfma_f32_16x16x32_bf16 v[66:69], v[228:231], v[212:215], v[66:69]
	s_setprio 0
	s_mov_b32 m0, s13
	v_lshl_add_u64 v[232:233], v[236:237], 0, s[94:95]
	s_barrier
	ds_read_b128 v[172:175], v154 offset:49152
	ds_read_b128 v[188:191], v154 offset:50176
	ds_read_b128 v[192:195], v154 offset:51200
	ds_read_b128 v[196:199], v154 offset:52224
	ds_read_b128 v[200:203], v154 offset:53248
	ds_read_b128 v[204:207], v154 offset:54272
	ds_read_b128 v[208:211], v154 offset:55296
	ds_read_b128 v[212:215], v154 offset:56320
	global_load_lds_dwordx4 v[232:233], off
	v_lshl_add_u64 v[232:233], v[238:239], 0, s[94:95]
	s_mov_b32 m0, s14
	s_nop 0
	global_load_lds_dwordx4 v[232:233], off
	s_barrier
; #define PG8_STAGE(bufoff, gbase, voff) do { _Pragma("unroll") for (int _i = 0; _i < 2; ++_i) \
;         __builtin_amdgcn_global_load_lds((const unsigned*)((const char*)(gbase) + (voff)[_i]), (LAS unsigned*)(lds + (bufoff) + ldsw + _i * 8192), 16, 0, 0); } while (0)
; #define PG8_MMA(ai, bj, At, Bt) do { __builtin_amdgcn_s_setprio(1); _Pragma("unroll") for (int m = 0; m < 4; ++m) _Pragma("unroll") for (int n = 0; n < 2; ++n) _Pragma("unroll") for (int k = 0; k < 2; ++k) \
;         acc[ai][bj][m][n] = __builtin_amdgcn_mfma_f32_16x16x32_bf16(Bt[n][k], At[m][k], acc[ai][bj][m][n], 0, 0, 0); __builtin_amdgcn_s_setprio(0); } while (0)
; #define PG8_WAIT_V(n) asm volatile("s_waitcnt vmcnt(" #n ")" ::: "memory")
; #define PG8_WAIT_L(n) asm volatile("s_waitcnt lgkmcnt(" #n ")" ::: "memory")
; #define PG8_BAR __builtin_amdgcn_s_barrier()
; #define PG8_SCHED __builtin_amdgcn_sched_barrier(0)
; template <class Epi, class Sched>
; __device__ __forceinline__ void gemm_phase(LAS unsigned char* lds, const Gemm g, const Sched& S, const Epi& E) {
;     ...
;             PG8_BAR; PG8_WAIT_L(0); PG8_MMA(1, 0, At, B0); PG8_BAR; PG8_SCHED;
;             PG8_STAGE(PG8_SB(1, 1), b3 + hstep, voffB);
;             PG8_WAIT_V(6); PG8_BAR; PG8_MMA(1, 1, At, B1); PG8_BAR;
	s_waitcnt lgkmcnt(0)
	s_setprio 1
	s_waitcnt lgkmcnt(0)
	v_mfma_f32_16x16x32_bf16 v[62:65], v[156:159], v[172:175], v[62:65]
	v_mfma_f32_16x16x32_bf16 v[58:61], v[164:167], v[172:175], v[58:61]
	v_mfma_f32_16x16x32_bf16 v[54:57], v[156:159], v[192:195], v[54:57]
	v_mfma_f32_16x16x32_bf16 v[50:53], v[164:167], v[192:195], v[50:53]
	v_mfma_f32_16x16x32_bf16 v[38:41], v[156:159], v[200:203], v[38:41]
	v_mfma_f32_16x16x32_bf16 v[34:37], v[164:167], v[200:203], v[34:37]
	v_mfma_f32_16x16x32_bf16 v[22:25], v[156:159], v[208:211], v[22:25]
	v_mfma_f32_16x16x32_bf16 v[18:21], v[164:167], v[208:211], v[18:21]
	v_mfma_f32_16x16x32_bf16 v[62:65], v[160:163], v[188:191], v[62:65]
	v_mfma_f32_16x16x32_bf16 v[58:61], v[168:171], v[188:191], v[58:61]
	v_mfma_f32_16x16x32_bf16 v[54:57], v[160:163], v[196:199], v[54:57]
	v_mfma_f32_16x16x32_bf16 v[50:53], v[168:171], v[196:199], v[50:53]
	v_mfma_f32_16x16x32_bf16 v[38:41], v[160:163], v[204:207], v[38:41]
	v_mfma_f32_16x16x32_bf16 v[34:37], v[168:171], v[204:207], v[34:37]
	v_mfma_f32_16x16x32_bf16 v[22:25], v[160:163], v[212:215], v[22:25]
	v_mfma_f32_16x16x32_bf16 v[18:21], v[168:171], v[212:215], v[18:21]
	s_setprio 0
	s_barrier
	s_add_u32 s20, s66, 0x40080
	s_addc_u32 s21, s67, 0
	s_add_i32 s22, s23, s9
	v_lshl_add_u64 v[156:157], s[20:21], 0, v[144:145]
	s_mov_b32 m0, s22
	s_nop 0
	global_load_lds_dwordx4 v[156:157], off
	v_lshl_add_u64 v[156:157], s[20:21], 0, v[140:141]
	s_add_i32 m0, s22, 0x2000
	s_nop 0
	global_load_lds_dwordx4 v[156:157], off
	s_waitcnt vmcnt(6)
	s_barrier
	s_setprio 1
	v_mfma_f32_16x16x32_bf16 v[46:49], v[216:219], v[172:175], v[46:49]
	v_mfma_f32_16x16x32_bf16 v[42:45], v[224:227], v[172:175], v[42:45]
	v_mfma_f32_16x16x32_bf16 v[30:33], v[216:219], v[192:195], v[30:33]
	v_mfma_f32_16x16x32_bf16 v[26:29], v[224:227], v[192:195], v[26:29]
	v_mfma_f32_16x16x32_bf16 v[14:17], v[216:219], v[200:203], v[14:17]
	v_mfma_f32_16x16x32_bf16 v[10:13], v[224:227], v[200:203], v[10:13]
	v_mfma_f32_16x16x32_bf16 v[4:7], v[216:219], v[208:211], v[4:7]
	v_mfma_f32_16x16x32_bf16 v[0:3], v[224:227], v[208:211], v[0:3]
	v_mfma_f32_16x16x32_bf16 v[46:49], v[220:223], v[188:191], v[46:49]
	v_mfma_f32_16x16x32_bf16 v[42:45], v[228:231], v[188:191], v[42:45]
	v_mfma_f32_16x16x32_bf16 v[30:33], v[220:223], v[196:199], v[30:33]
	v_mfma_f32_16x16x32_bf16 v[26:29], v[228:231], v[196:199], v[26:29]
	v_mfma_f32_16x16x32_bf16 v[14:17], v[220:223], v[204:207], v[14:17]
	v_mfma_f32_16x16x32_bf16 v[10:13], v[228:231], v[204:207], v[10:13]
	v_mfma_f32_16x16x32_bf16 v[4:7], v[220:223], v[212:215], v[4:7]
	v_mfma_f32_16x16x32_bf16 v[0:3], v[228:231], v[212:215], v[0:3]
	s_setprio 0
	s_add_i32 s19, s19, 2
	s_add_u32 vcc_lo, vcc_lo, 0x100
	s_addc_u32 vcc_hi, vcc_hi, 0
	s_add_u32 s74, s74, 0x100
	s_addc_u32 s18, s18, 0
	s_cmp_gt_u32 s19, 13
	s_barrier
	s_cbranch_scc0 .LBB0_515
; __device__ __forceinline__ unsigned pk_bf16(float a, float b) { f32x2 v = {a, b}; bf2_t r = __builtin_convertvector(v, bf2_t); return __builtin_bit_cast(unsigned, r); }
; #define PG8_WAIT_V(n) asm volatile("s_waitcnt vmcnt(" #n ")" ::: "memory")
; #define PG8_BAR __builtin_amdgcn_s_barrier()
;     __device__ __forceinline__ void operator()(const f32x4 (&acc)[2][2][4][2], const Unit& u, int wr, int wc, int fr, int fq) const {
;         const int row0 = u.pm * BM + wr * 64 + fr; int colt = u.pn * BM; bf16_t* base = O;
;         if (split_cols) { const int t = colt / split_cols; base += (size_t)t * split_stride; colt -= t * split_cols; }
;         const int col0 = colt + wc * 32 + 8 * fq;
; #pragma unroll
;         for (int ai = 0; ai < 2; ++ai)
; #pragma unroll
;             for (int m = 0; m < 4; ++m) { const int row = row0 + ai * HALF + m * 16;
;                 bf16_t* rowp = slot_stride ? base + (size_t)(colt >> 7) * slot_stride + (size_t)row * 128 + wc * 32 + 8 * fq : base + (size_t)row * ldc + col0;
; #pragma unroll
;                 for (int bj = 0; bj < 2; ++bj) { const f32x4 v0 = acc[ai][bj][m][0], v1 = acc[ai][bj][m][1];
;                     u32x4 w; w.x = pk_bf16(v0[0], v0[1]); w.y = pk_bf16(v0[2], v0[3]); w.z = pk_bf16(v1[0], v1[1]); w.w = pk_bf16(v1[2], v1[3]);
;                     *(u32x4*)(rowp + (slot_stride ? (size_t)bj * slot_stride : (size_t)bj * HALF)) = w; } }
; template <class Epi, class Sched>
; __device__ __forceinline__ void gemm_phase(LAS unsigned char* lds, const Gemm g, const Sched& S, const Epi& E) {
;     ...
;         E(acc, cur, wr, wc, fr, fq); S.done(cur);
;         if (!has_next) break;
; #pragma unroll
;         for (int a = 0; a < 2; ++a)
; #pragma unroll
;             for (int b = 0; b < 2; ++b)
; #pragma unroll
;                 for (int m = 0; m < 4; ++m)
; #pragma unroll
;                     for (int n = 0; n < 2; ++n) acc[a][b][m][n] = (f32x4){0.f, 0.f, 0.f, 0.f};
;         cur = nxt; cA = nA; cB = nB; ++ui;
;     }
;     PG8_WAIT_V(0);
;     if (wr == 0) PG8_BAR;
;     PG8_BAR;
	v_lshl_add_u32 v156, s40, 8, v9
	v_lshl_or_b32 v158, s0, 8, v153
	v_ashrrev_i32_e32 v159, 31, v158
	v_ashrrev_i32_e32 v157, 31, v156
	v_lshl_add_u64 v[158:159], v[158:159], 1, s[82:83]
	v_lshlrev_b64 v[160:161], 11, v[156:157]
	v_lshl_add_u64 v[160:161], v[158:159], 0, v[160:161]
	s_mov_b32 s0, 0x40000
	s_mov_b64 s[16:17], 0x40000
	v_cvt_pk_bf16_f32 v62, v62, v63
	v_cvt_pk_bf16_f32 v63, v64, v65
	v_cvt_pk_bf16_f32 v64, v58, v59
	v_add_co_u32_e32 v58, vcc, s0, v160
	v_cvt_pk_bf16_f32 v70, v70, v71
	v_cvt_pk_bf16_f32 v71, v72, v73
	v_cvt_pk_bf16_f32 v72, v66, v67
	v_lshl_add_u64 v[66:67], v[160:161], 0, s[16:17]
	v_addc_co_u32_e32 v59, vcc, 0, v161, vcc
	v_cvt_pk_bf16_f32 v46, v46, v47
	v_cvt_pk_bf16_f32 v47, v48, v49
	v_cvt_pk_bf16_f32 v48, v42, v43
	v_cvt_pk_bf16_f32 v49, v44, v45
	s_mov_b32 s0, 0x48000
	global_store_dwordx4 v[66:67], v[46:49], off offset:256
	s_mov_b64 s[16:17], 0x48000
	v_cvt_pk_bf16_f32 v110, v110, v111
	v_add_co_u32_e32 v48, vcc, s0, v160
	v_cvt_pk_bf16_f32 v111, v112, v113
	v_cvt_pk_bf16_f32 v112, v106, v107
	v_or_b32_e32 v106, 16, v156
	v_lshl_add_u64 v[46:47], v[160:161], 0, s[16:17]
	v_addc_co_u32_e32 v49, vcc, 0, v161, vcc
	v_cvt_pk_bf16_f32 v30, v30, v31
	v_cvt_pk_bf16_f32 v31, v32, v33
	v_cvt_pk_bf16_f32 v32, v26, v27
	v_cvt_pk_bf16_f32 v33, v28, v29
	s_mov_b32 s0, 0x50000
	v_ashrrev_i32_e32 v107, 31, v106
	v_cvt_pk_bf16_f32 v94, v94, v95
	v_cvt_pk_bf16_f32 v95, v96, v97
	v_cvt_pk_bf16_f32 v96, v90, v91
	v_or_b32_e32 v90, 32, v156
	global_store_dwordx4 v[46:47], v[30:33], off offset:256
	s_mov_b64 s[16:17], 0x50000
	v_cvt_pk_bf16_f32 v113, v108, v109
	v_add_co_u32_e32 v32, vcc, s0, v160
	v_lshlrev_b64 v[106:107], 11, v[106:107]
	v_ashrrev_i32_e32 v91, 31, v90
	v_cvt_pk_bf16_f32 v78, v78, v79
	v_cvt_pk_bf16_f32 v79, v80, v81
	v_cvt_pk_bf16_f32 v80, v74, v75
	v_or_b32_e32 v74, 48, v156
	v_lshl_add_u64 v[30:31], v[160:161], 0, s[16:17]
	v_addc_co_u32_e32 v33, vcc, 0, v161, vcc
	v_cvt_pk_bf16_f32 v14, v14, v15
	v_cvt_pk_bf16_f32 v15, v16, v17
	v_cvt_pk_bf16_f32 v16, v10, v11
	v_cvt_pk_bf16_f32 v17, v12, v13
	s_mov_b32 s0, 0x58000
	global_store_dwordx4 v[160:161], v[110:113], off offset:256
	v_cvt_pk_bf16_f32 v97, v92, v93
	v_lshlrev_b64 v[90:91], 11, v[90:91]
	v_lshl_add_u64 v[110:111], v[158:159], 0, v[106:107]
	v_ashrrev_i32_e32 v75, 31, v74
	global_store_dwordx4 v[30:31], v[14:17], off offset:256
	global_store_dwordx4 v[110:111], v[94:97], off offset:256
	v_cvt_pk_bf16_f32 v81, v76, v77
	v_add_co_u32_e32 v16, vcc, s0, v160
	v_lshl_add_u64 v[94:95], v[158:159], 0, v[90:91]
	v_lshlrev_b64 v[74:75], 11, v[74:75]
	s_mov_b64 s[16:17], 0x58000
	v_addc_co_u32_e32 v17, vcc, 0, v161, vcc
	v_cvt_pk_bf16_f32 v126, v126, v127
	v_cvt_pk_bf16_f32 v127, v128, v129
	v_cvt_pk_bf16_f32 v128, v122, v123
	v_cvt_pk_bf16_f32 v129, v124, v125
	v_cvt_pk_bf16_f32 v106, v118, v119
	v_cvt_pk_bf16_f32 v107, v120, v121
	v_cvt_pk_bf16_f32 v108, v114, v115
	v_cvt_pk_bf16_f32 v109, v116, v117
	v_cvt_pk_bf16_f32 v90, v102, v103
	v_cvt_pk_bf16_f32 v91, v104, v105
	v_cvt_pk_bf16_f32 v92, v98, v99
	v_cvt_pk_bf16_f32 v93, v100, v101
	global_store_dwordx4 v[94:95], v[78:81], off offset:256
	v_cvt_pk_bf16_f32 v76, v82, v83
	v_cvt_pk_bf16_f32 v77, v84, v85
	v_lshl_add_u64 v[78:79], v[158:159], 0, v[74:75]
	v_cvt_pk_bf16_f32 v74, v86, v87
	v_cvt_pk_bf16_f32 v75, v88, v89
	v_cvt_pk_bf16_f32 v73, v68, v69
	v_cvt_pk_bf16_f32 v65, v60, v61
	v_cvt_pk_bf16_f32 v42, v54, v55
	v_cvt_pk_bf16_f32 v43, v56, v57
	v_cvt_pk_bf16_f32 v44, v50, v51
	v_cvt_pk_bf16_f32 v45, v52, v53
	v_cvt_pk_bf16_f32 v26, v38, v39
	v_cvt_pk_bf16_f32 v27, v40, v41
	v_cvt_pk_bf16_f32 v28, v34, v35
	v_cvt_pk_bf16_f32 v29, v36, v37
	v_lshl_add_u64 v[14:15], v[160:161], 0, s[16:17]
	v_cvt_pk_bf16_f32 v10, v22, v23
	v_cvt_pk_bf16_f32 v11, v24, v25
	v_cvt_pk_bf16_f32 v12, v18, v19
	v_cvt_pk_bf16_f32 v13, v20, v21
	v_cvt_pk_bf16_f32 v4, v4, v5
	v_cvt_pk_bf16_f32 v5, v6, v7
	v_cvt_pk_bf16_f32 v6, v0, v1
	v_cvt_pk_bf16_f32 v7, v2, v3
	s_and_b64 vcc, exec, s[38:39]
	s_mov_b32 s0, s42
	s_mov_b32 s40, s88
	s_mov_b64 s[74:75], s[70:71]
	s_mov_b64 s[72:73], s[78:79]
	global_store_dwordx4 v[160:161], v[126:129], off
	global_store_dwordx4 v[110:111], v[106:109], off
	global_store_dwordx4 v[94:95], v[90:93], off
	global_store_dwordx4 v[78:79], v[74:77], off
	global_store_dwordx4 v[78:79], v[70:73], off offset:256
	global_store_dwordx4 v[58:59], v[62:65], off
	global_store_dwordx4 v[48:49], v[42:45], off
	global_store_dwordx4 v[32:33], v[26:29], off
	global_store_dwordx4 v[16:17], v[10:13], off
	global_store_dwordx4 v[14:15], v[4:7], off offset:256
	s_cbranch_vccz .LBB0_512
	s_waitcnt vmcnt(0)
	s_cmpk_gt_u32 s6, 0xff
	s_cbranch_scc1 .LBB0_519
	s_barrier

; #define PG8_STAGE(bufoff, gbase, voff) do { _Pragma("unroll") for (int _i = 0; _i < 2; ++_i) \
;         __builtin_amdgcn_global_load_lds((const unsigned*)((const char*)(gbase) + (voff)[_i]), (LAS unsigned*)(lds + (bufoff) + ldsw + _i * 8192), 16, 0, 0); } while (0)
; #define PG8_LDA(dst, b, h) do { _Pragma("unroll") for (int m = 0; m < 4; ++m) _Pragma("unroll") for (int k = 0; k < 2; ++k) dst[m][k] = *(const LAS bf16x8*)(lds + PG8_SA(b, h) + aoff + m * 2048 + k * 1024); } while (0)
; #define PG8_LDB(dst, b, h) do { _Pragma("unroll") for (int n = 0; n < 2; ++n) _Pragma("unroll") for (int k = 0; k < 2; ++k) dst[n][k] = *(const LAS bf16x8*)(lds + PG8_SB(b, h) + boff + n * 2048 + k * 1024); } while (0)
; #define PG8_MMA(ai, bj, At, Bt) do { __builtin_amdgcn_s_setprio(1); _Pragma("unroll") for (int m = 0; m < 4; ++m) _Pragma("unroll") for (int n = 0; n < 2; ++n) _Pragma("unroll") for (int k = 0; k < 2; ++k) \
;         acc[ai][bj][m][n] = __builtin_amdgcn_mfma_f32_16x16x32_bf16(Bt[n][k], At[m][k], acc[ai][bj][m][n], 0, 0, 0); __builtin_amdgcn_s_setprio(0); } while (0)
; #define PG8_WAIT_L(n) asm volatile("s_waitcnt lgkmcnt(" #n ")" ::: "memory")
; #define PG8_BAR __builtin_amdgcn_s_barrier()
; #define PG8_SCHED __builtin_amdgcn_sched_barrier(0)
; template <class Epi, class Sched>
; __device__ __forceinline__ void gemm_phase(LAS unsigned char* lds, const Gemm g, const Sched& S, const Epi& E) {
;     ...
;         for (int t = 0; t < nt; t += 2) {
;             const bool last = (t == nt - 2);
;             const char* a1 = cA + (size_t)(t + 1) * kstep;
;             const char* a2 = last ? nA : cA + (size_t)(t + 2) * kstep; const char* b2 = last ? nB : cB + (size_t)(t + 2) * kstep;
;             const char* a3 = a2 + kstep; const char* b3 = b2 + kstep;
;             if (last && has_next) S.a_ready(nxt);
;             PG8_LDB(B0, 0, 0); PG8_SCHED; PG8_LDA(At, 0, 0); PG8_STAGE(PG8_SA(1, 1), a1 + hstep, voffA);
;             PG8_WAIT_L(8); PG8_BAR; PG8_WAIT_L(0); PG8_MMA(0, 0, At, B0); PG8_BAR; PG8_SCHED;
;             PG8_LDB(B1, 0, 1); PG8_STAGE(PG8_SB(0, 0), b2, voffB);
;             PG8_BAR; PG8_WAIT_L(0); PG8_MMA(0, 1, At, B1); PG8_BAR;
;             PG8_LDA(At, 0, 1); PG8_STAGE(PG8_SA(0, 0), a2, voffA);
;             PG8_BAR; PG8_WAIT_L(0); PG8_MMA(1, 0, At, B0); PG8_BAR; PG8_SCHED;
.LBB0_646:
	s_add_u32 s21, vcc_lo, 0xfffc0080
	s_addc_u32 s22, vcc_hi, -1
	s_add_i32 s23, 16, 0x10000
	v_add_u32_e32 v155, s23, v152
	ds_read_b128 v[156:159], v155
	ds_read_b128 v[160:163], v155 offset:1024
	ds_read_b128 v[164:167], v155 offset:2048
	ds_read_b128 v[168:171], v155 offset:3072
	s_cmp_eq_u32 s20, 12
	s_cselect_b32 s79, s75, s22
	s_cselect_b32 s78, s16, s21
	s_cselect_b32 s71, s17, s19
	s_cselect_b32 s70, s73, s18
	v_lshl_add_u64 v[216:217], vcc, 0, v[148:149]
	s_add_i32 m0, s11, 0xc000
	ds_read_b128 v[172:175], v154
	ds_read_b128 v[188:191], v154 offset:1024
	ds_read_b128 v[192:195], v154 offset:2048
	ds_read_b128 v[196:199], v154 offset:3072
	ds_read_b128 v[200:203], v154 offset:4096
	ds_read_b128 v[204:207], v154 offset:5120
	ds_read_b128 v[208:211], v154 offset:6144
	ds_read_b128 v[212:215], v154 offset:7168
	global_load_lds_dwordx4 v[216:217], off
	v_lshl_add_u64 v[216:217], vcc, 0, v[150:151]
	s_add_i32 m0, s11, 0xe000
	s_nop 0
	global_load_lds_dwordx4 v[216:217], off
	s_barrier
	s_waitcnt lgkmcnt(0)
	s_setprio 1
	s_waitcnt lgkmcnt(0)
	v_mfma_f32_16x16x32_bf16 v[126:129], v[156:159], v[172:175], v[126:129]
	v_mfma_f32_16x16x32_bf16 v[122:125], v[164:167], v[172:175], v[122:125]
	v_mfma_f32_16x16x32_bf16 v[118:121], v[156:159], v[192:195], v[118:121]
	v_mfma_f32_16x16x32_bf16 v[114:117], v[164:167], v[192:195], v[114:117]
	v_mfma_f32_16x16x32_bf16 v[102:105], v[156:159], v[200:203], v[102:105]
	v_mfma_f32_16x16x32_bf16 v[98:101], v[164:167], v[200:203], v[98:101]
	v_mfma_f32_16x16x32_bf16 v[86:89], v[156:159], v[208:211], v[86:89]
	v_mfma_f32_16x16x32_bf16 v[82:85], v[164:167], v[208:211], v[82:85]
	v_mfma_f32_16x16x32_bf16 v[126:129], v[160:163], v[188:191], v[126:129]
	v_mfma_f32_16x16x32_bf16 v[122:125], v[168:171], v[188:191], v[122:125]
	v_mfma_f32_16x16x32_bf16 v[118:121], v[160:163], v[196:199], v[118:121]
	v_mfma_f32_16x16x32_bf16 v[114:117], v[168:171], v[196:199], v[114:117]
	v_mfma_f32_16x16x32_bf16 v[102:105], v[160:163], v[204:207], v[102:105]
	v_mfma_f32_16x16x32_bf16 v[98:101], v[168:171], v[204:207], v[98:101]
	v_mfma_f32_16x16x32_bf16 v[86:89], v[160:163], v[212:215], v[86:89]
	v_mfma_f32_16x16x32_bf16 v[82:85], v[168:171], v[212:215], v[82:85]
	s_setprio 0
	s_barrier
	s_add_i32 s21, 16, 0x14000
	s_add_i32 s22, s23, s9
	v_add_u32_e32 v155, s21, v152
	v_lshl_add_u64 v[232:233], s[70:71], 0, v[144:145]
	s_mov_b32 m0, s22
	ds_read_b128 v[216:219], v155
	ds_read_b128 v[220:223], v155 offset:1024
	ds_read_b128 v[224:227], v155 offset:2048
	ds_read_b128 v[228:231], v155 offset:3072
	global_load_lds_dwordx4 v[232:233], off
	v_lshl_add_u64 v[234:235], s[70:71], 0, v[140:141]
	s_add_i32 m0, s22, 0x2000
	s_nop 0
	global_load_lds_dwordx4 v[234:235], off
	s_barrier
	s_waitcnt lgkmcnt(0)
	s_setprio 1
	s_waitcnt lgkmcnt(0)
	v_mfma_f32_16x16x32_bf16 v[110:113], v[216:219], v[172:175], v[110:113]
	v_mfma_f32_16x16x32_bf16 v[106:109], v[224:227], v[172:175], v[106:109]
	v_mfma_f32_16x16x32_bf16 v[94:97], v[216:219], v[192:195], v[94:97]
	v_mfma_f32_16x16x32_bf16 v[90:93], v[224:227], v[192:195], v[90:93]
	v_mfma_f32_16x16x32_bf16 v[78:81], v[216:219], v[200:203], v[78:81]
	v_mfma_f32_16x16x32_bf16 v[74:77], v[224:227], v[200:203], v[74:77]
	v_mfma_f32_16x16x32_bf16 v[70:73], v[216:219], v[208:211], v[70:73]
	v_mfma_f32_16x16x32_bf16 v[66:69], v[224:227], v[208:211], v[66:69]
	v_mfma_f32_16x16x32_bf16 v[110:113], v[220:223], v[188:191], v[110:113]
	v_mfma_f32_16x16x32_bf16 v[106:109], v[228:231], v[188:191], v[106:109]
	v_mfma_f32_16x16x32_bf16 v[94:97], v[220:223], v[196:199], v[94:97]
	v_mfma_f32_16x16x32_bf16 v[90:93], v[228:231], v[196:199], v[90:93]
	v_mfma_f32_16x16x32_bf16 v[78:81], v[220:223], v[204:207], v[78:81]
	v_mfma_f32_16x16x32_bf16 v[74:77], v[228:231], v[204:207], v[74:77]
	v_mfma_f32_16x16x32_bf16 v[70:73], v[220:223], v[212:215], v[70:73]
	v_mfma_f32_16x16x32_bf16 v[66:69], v[228:231], v[212:215], v[66:69]
	s_setprio 0
	s_mov_b32 m0, s11
	v_lshl_add_u64 v[236:237], s[78:79], 0, v[146:147]
	s_barrier
	ds_read_b128 v[172:175], v154 offset:16384
	ds_read_b128 v[188:191], v154 offset:17408
	ds_read_b128 v[192:195], v154 offset:18432
	ds_read_b128 v[196:199], v154 offset:19456
	ds_read_b128 v[200:203], v154 offset:20480
	ds_read_b128 v[204:207], v154 offset:21504
	ds_read_b128 v[208:211], v154 offset:22528
	ds_read_b128 v[212:215], v154 offset:23552
	global_load_lds_dwordx4 v[236:237], off
	v_lshl_add_u64 v[238:239], s[78:79], 0, v[142:143]
	s_mov_b32 m0, s41
	s_nop 0
	global_load_lds_dwordx4 v[238:239], off
	s_barrier
	s_waitcnt lgkmcnt(0)
	s_setprio 1
	s_waitcnt lgkmcnt(0)
	v_mfma_f32_16x16x32_bf16 v[62:65], v[156:159], v[172:175], v[62:65]
	v_mfma_f32_16x16x32_bf16 v[58:61], v[164:167], v[172:175], v[58:61]
	v_mfma_f32_16x16x32_bf16 v[54:57], v[156:159], v[192:195], v[54:57]
	v_mfma_f32_16x16x32_bf16 v[50:53], v[164:167], v[192:195], v[50:53]
	v_mfma_f32_16x16x32_bf16 v[38:41], v[156:159], v[200:203], v[38:41]
	v_mfma_f32_16x16x32_bf16 v[34:37], v[164:167], v[200:203], v[34:37]
	v_mfma_f32_16x16x32_bf16 v[22:25], v[156:159], v[208:211], v[22:25]
	v_mfma_f32_16x16x32_bf16 v[18:21], v[164:167], v[208:211], v[18:21]
	v_mfma_f32_16x16x32_bf16 v[62:65], v[160:163], v[188:191], v[62:65]
	v_mfma_f32_16x16x32_bf16 v[58:61], v[168:171], v[188:191], v[58:61]
	v_mfma_f32_16x16x32_bf16 v[54:57], v[160:163], v[196:199], v[54:57]
	v_mfma_f32_16x16x32_bf16 v[50:53], v[168:171], v[196:199], v[50:53]
	v_mfma_f32_16x16x32_bf16 v[38:41], v[160:163], v[204:207], v[38:41]
	v_mfma_f32_16x16x32_bf16 v[34:37], v[168:171], v[204:207], v[34:37]
	v_mfma_f32_16x16x32_bf16 v[22:25], v[160:163], v[212:215], v[22:25]
	v_mfma_f32_16x16x32_bf16 v[18:21], v[168:171], v[212:215], v[18:21]
	s_setprio 0
	s_barrier
; #define PG8_STAGE(bufoff, gbase, voff) do { _Pragma("unroll") for (int _i = 0; _i < 2; ++_i) \
;         __builtin_amdgcn_global_load_lds((const unsigned*)((const char*)(gbase) + (voff)[_i]), (LAS unsigned*)(lds + (bufoff) + ldsw + _i * 8192), 16, 0, 0); } while (0)
; #define PG8_LDA(dst, b, h) do { _Pragma("unroll") for (int m = 0; m < 4; ++m) _Pragma("unroll") for (int k = 0; k < 2; ++k) dst[m][k] = *(const LAS bf16x8*)(lds + PG8_SA(b, h) + aoff + m * 2048 + k * 1024); } while (0)
; #define PG8_LDB(dst, b, h) do { _Pragma("unroll") for (int n = 0; n < 2; ++n) _Pragma("unroll") for (int k = 0; k < 2; ++k) dst[n][k] = *(const LAS bf16x8*)(lds + PG8_SB(b, h) + boff + n * 2048 + k * 1024); } while (0)
; #define PG8_MMA(ai, bj, At, Bt) do { __builtin_amdgcn_s_setprio(1); _Pragma("unroll") for (int m = 0; m < 4; ++m) _Pragma("unroll") for (int n = 0; n < 2; ++n) _Pragma("unroll") for (int k = 0; k < 2; ++k) \
;         acc[ai][bj][m][n] = __builtin_amdgcn_mfma_f32_16x16x32_bf16(Bt[n][k], At[m][k], acc[ai][bj][m][n], 0, 0, 0); __builtin_amdgcn_s_setprio(0); } while (0)
; #define PG8_WAIT_V(n) asm volatile("s_waitcnt vmcnt(" #n ")" ::: "memory")
; #define PG8_WAIT_L(n) asm volatile("s_waitcnt lgkmcnt(" #n ")" ::: "memory")
; #define PG8_BAR __builtin_amdgcn_s_barrier()
; #define PG8_SCHED __builtin_amdgcn_sched_barrier(0)
; template <class Epi, class Sched>
; __device__ __forceinline__ void gemm_phase(LAS unsigned char* lds, const Gemm g, const Sched& S, const Epi& E) {
;     ...
;             PG8_STAGE(PG8_SB(0, 1), b2 + hstep, voffB);
;             PG8_WAIT_V(6); PG8_BAR; PG8_MMA(1, 1, At, B1); PG8_BAR;
;             PG8_LDB(B0, 1, 0); PG8_SCHED; PG8_LDA(At, 1, 0); PG8_STAGE(PG8_SA(0, 1), a2 + hstep, voffA);
;             PG8_WAIT_L(8); PG8_BAR; PG8_WAIT_L(0); PG8_MMA(0, 0, At, B0); PG8_BAR; PG8_SCHED;
;             PG8_LDB(B1, 1, 1); PG8_STAGE(PG8_SB(1, 0), b3, voffB);
;             PG8_BAR; PG8_WAIT_L(0); PG8_MMA(0, 1, At, B1); PG8_BAR;
;             PG8_LDA(At, 1, 1); PG8_STAGE(PG8_SA(1, 0), a3, voffA);
	s_add_u32 s22, s70, 0x40000
	s_addc_u32 s23, s71, 0
	s_add_i32 s21, s21, s9
	v_lshl_add_u64 v[156:157], s[22:23], 0, v[144:145]
	s_mov_b32 m0, s21
	s_nop 0
	global_load_lds_dwordx4 v[156:157], off
	v_lshl_add_u64 v[156:157], s[22:23], 0, v[140:141]
	s_add_i32 m0, s21, 0x2000
	s_nop 0
	global_load_lds_dwordx4 v[156:157], off
	s_waitcnt vmcnt(6)
	s_barrier
	s_setprio 1
	v_mfma_f32_16x16x32_bf16 v[46:49], v[216:219], v[172:175], v[46:49]
	v_mfma_f32_16x16x32_bf16 v[42:45], v[224:227], v[172:175], v[42:45]
	v_mfma_f32_16x16x32_bf16 v[30:33], v[216:219], v[192:195], v[30:33]
	v_mfma_f32_16x16x32_bf16 v[26:29], v[224:227], v[192:195], v[26:29]
	v_mfma_f32_16x16x32_bf16 v[14:17], v[216:219], v[200:203], v[14:17]
	v_mfma_f32_16x16x32_bf16 v[10:13], v[224:227], v[200:203], v[10:13]
	v_mfma_f32_16x16x32_bf16 v[4:7], v[216:219], v[208:211], v[4:7]
	v_mfma_f32_16x16x32_bf16 v[0:3], v[224:227], v[208:211], v[0:3]
	v_mfma_f32_16x16x32_bf16 v[46:49], v[220:223], v[188:191], v[46:49]
	v_mfma_f32_16x16x32_bf16 v[42:45], v[228:231], v[188:191], v[42:45]
	v_mfma_f32_16x16x32_bf16 v[30:33], v[220:223], v[196:199], v[30:33]
	v_mfma_f32_16x16x32_bf16 v[26:29], v[228:231], v[196:199], v[26:29]
	v_mfma_f32_16x16x32_bf16 v[14:17], v[220:223], v[204:207], v[14:17]
	v_mfma_f32_16x16x32_bf16 v[10:13], v[228:231], v[204:207], v[10:13]
	v_mfma_f32_16x16x32_bf16 v[4:7], v[220:223], v[212:215], v[4:7]
	v_mfma_f32_16x16x32_bf16 v[0:3], v[228:231], v[212:215], v[0:3]
	s_setprio 0
	s_add_i32 s21, 16, 0x18000
	v_add_u32_e32 v155, s21, v152
	s_barrier
	ds_read_b128 v[156:159], v155
	ds_read_b128 v[160:163], v155 offset:1024
	ds_read_b128 v[164:167], v155 offset:2048
	ds_read_b128 v[168:171], v155 offset:3072
	s_add_u32 s22, s78, 0x40000
	s_addc_u32 s23, s79, 0
	s_mov_b32 m0, s12
	v_lshl_add_u64 v[216:217], s[22:23], 0, v[146:147]
	ds_read_b128 v[172:175], v154 offset:32768
	ds_read_b128 v[188:191], v154 offset:33792
	ds_read_b128 v[192:195], v154 offset:34816
	ds_read_b128 v[196:199], v154 offset:35840
	ds_read_b128 v[200:203], v154 offset:36864
	ds_read_b128 v[204:207], v154 offset:37888
	ds_read_b128 v[208:211], v154 offset:38912
	ds_read_b128 v[212:215], v154 offset:39936
	global_load_lds_dwordx4 v[216:217], off
	v_lshl_add_u64 v[216:217], s[22:23], 0, v[142:143]
	s_mov_b32 m0, s13
	s_nop 0
	global_load_lds_dwordx4 v[216:217], off
	s_barrier
	s_waitcnt lgkmcnt(0)
	s_setprio 1
	s_waitcnt lgkmcnt(0)
	v_mfma_f32_16x16x32_bf16 v[126:129], v[156:159], v[172:175], v[126:129]
	v_mfma_f32_16x16x32_bf16 v[122:125], v[164:167], v[172:175], v[122:125]
	v_mfma_f32_16x16x32_bf16 v[118:121], v[156:159], v[192:195], v[118:121]
	v_mfma_f32_16x16x32_bf16 v[114:117], v[164:167], v[192:195], v[114:117]
	v_mfma_f32_16x16x32_bf16 v[102:105], v[156:159], v[200:203], v[102:105]
	v_mfma_f32_16x16x32_bf16 v[98:101], v[164:167], v[200:203], v[98:101]
	v_mfma_f32_16x16x32_bf16 v[86:89], v[156:159], v[208:211], v[86:89]
	v_mfma_f32_16x16x32_bf16 v[82:85], v[164:167], v[208:211], v[82:85]
	v_mfma_f32_16x16x32_bf16 v[126:129], v[160:163], v[188:191], v[126:129]
	v_mfma_f32_16x16x32_bf16 v[122:125], v[168:171], v[188:191], v[122:125]
	v_mfma_f32_16x16x32_bf16 v[118:121], v[160:163], v[196:199], v[118:121]
	v_mfma_f32_16x16x32_bf16 v[114:117], v[168:171], v[196:199], v[114:117]
	v_mfma_f32_16x16x32_bf16 v[102:105], v[160:163], v[204:207], v[102:105]
	v_mfma_f32_16x16x32_bf16 v[98:101], v[168:171], v[204:207], v[98:101]
	v_mfma_f32_16x16x32_bf16 v[86:89], v[160:163], v[212:215], v[86:89]
	v_mfma_f32_16x16x32_bf16 v[82:85], v[168:171], v[212:215], v[82:85]
	s_setprio 0
	s_barrier
	s_add_i32 s78, 16, 0x1c000
	s_add_i32 s21, s21, s9
	v_add_u32_e32 v155, s78, v152
	v_lshl_add_u64 v[232:233], v[232:233], 0, s[94:95]
	s_mov_b32 m0, s21
	ds_read_b128 v[216:219], v155
	ds_read_b128 v[220:223], v155 offset:1024
	ds_read_b128 v[224:227], v155 offset:2048
	ds_read_b128 v[228:231], v155 offset:3072
	global_load_lds_dwordx4 v[232:233], off
	v_lshl_add_u64 v[232:233], v[234:235], 0, s[94:95]
	s_add_i32 m0, s21, 0x2000
	s_nop 0
	global_load_lds_dwordx4 v[232:233], off
	s_barrier
	s_waitcnt lgkmcnt(0)
	s_setprio 1
	s_waitcnt lgkmcnt(0)
	v_mfma_f32_16x16x32_bf16 v[110:113], v[216:219], v[172:175], v[110:113]
	v_mfma_f32_16x16x32_bf16 v[106:109], v[224:227], v[172:175], v[106:109]
	v_mfma_f32_16x16x32_bf16 v[94:97], v[216:219], v[192:195], v[94:97]
	v_mfma_f32_16x16x32_bf16 v[90:93], v[224:227], v[192:195], v[90:93]
	v_mfma_f32_16x16x32_bf16 v[78:81], v[216:219], v[200:203], v[78:81]
	v_mfma_f32_16x16x32_bf16 v[74:77], v[224:227], v[200:203], v[74:77]
	v_mfma_f32_16x16x32_bf16 v[70:73], v[216:219], v[208:211], v[70:73]
	v_mfma_f32_16x16x32_bf16 v[66:69], v[224:227], v[208:211], v[66:69]
	v_mfma_f32_16x16x32_bf16 v[110:113], v[220:223], v[188:191], v[110:113]
	v_mfma_f32_16x16x32_bf16 v[106:109], v[228:231], v[188:191], v[106:109]
	v_mfma_f32_16x16x32_bf16 v[94:97], v[220:223], v[196:199], v[94:97]
	v_mfma_f32_16x16x32_bf16 v[90:93], v[228:231], v[196:199], v[90:93]
	v_mfma_f32_16x16x32_bf16 v[78:81], v[220:223], v[204:207], v[78:81]
	v_mfma_f32_16x16x32_bf16 v[74:77], v[228:231], v[204:207], v[74:77]
	v_mfma_f32_16x16x32_bf16 v[70:73], v[220:223], v[212:215], v[70:73]
	v_mfma_f32_16x16x32_bf16 v[66:69], v[228:231], v[212:215], v[66:69]
	s_setprio 0
	s_mov_b32 m0, s14
	v_lshl_add_u64 v[232:233], v[236:237], 0, s[94:95]
	s_barrier
	ds_read_b128 v[172:175], v154 offset:49152
	ds_read_b128 v[188:191], v154 offset:50176
	ds_read_b128 v[192:195], v154 offset:51200
	ds_read_b128 v[196:199], v154 offset:52224
	ds_read_b128 v[200:203], v154 offset:53248
	ds_read_b128 v[204:207], v154 offset:54272
	ds_read_b128 v[208:211], v154 offset:55296
	ds_read_b128 v[212:215], v154 offset:56320
	global_load_lds_dwordx4 v[232:233], off
	v_lshl_add_u64 v[232:233], v[238:239], 0, s[94:95]
	s_mov_b32 m0, s15
	s_nop 0
	global_load_lds_dwordx4 v[232:233], off
	s_barrier
; #define PG8_STAGE(bufoff, gbase, voff) do { _Pragma("unroll") for (int _i = 0; _i < 2; ++_i) \
;         __builtin_amdgcn_global_load_lds((const unsigned*)((const char*)(gbase) + (voff)[_i]), (LAS unsigned*)(lds + (bufoff) + ldsw + _i * 8192), 16, 0, 0); } while (0)
; #define PG8_MMA(ai, bj, At, Bt) do { __builtin_amdgcn_s_setprio(1); _Pragma("unroll") for (int m = 0; m < 4; ++m) _Pragma("unroll") for (int n = 0; n < 2; ++n) _Pragma("unroll") for (int k = 0; k < 2; ++k) \
;         acc[ai][bj][m][n] = __builtin_amdgcn_mfma_f32_16x16x32_bf16(Bt[n][k], At[m][k], acc[ai][bj][m][n], 0, 0, 0); __builtin_amdgcn_s_setprio(0); } while (0)
; #define PG8_WAIT_V(n) asm volatile("s_waitcnt vmcnt(" #n ")" ::: "memory")
; #define PG8_WAIT_L(n) asm volatile("s_waitcnt lgkmcnt(" #n ")" ::: "memory")
; #define PG8_BAR __builtin_amdgcn_s_barrier()
; #define PG8_SCHED __builtin_amdgcn_sched_barrier(0)
; template <class Epi, class Sched>
; __device__ __forceinline__ void gemm_phase(LAS unsigned char* lds, const Gemm g, const Sched& S, const Epi& E) {
;     ...
;             PG8_BAR; PG8_WAIT_L(0); PG8_MMA(1, 0, At, B0); PG8_BAR; PG8_SCHED;
;             PG8_STAGE(PG8_SB(1, 1), b3 + hstep, voffB);
;             PG8_WAIT_V(6); PG8_BAR; PG8_MMA(1, 1, At, B1); PG8_BAR;
	s_waitcnt lgkmcnt(0)
	s_setprio 1
	s_waitcnt lgkmcnt(0)
	v_mfma_f32_16x16x32_bf16 v[62:65], v[156:159], v[172:175], v[62:65]
	v_mfma_f32_16x16x32_bf16 v[58:61], v[164:167], v[172:175], v[58:61]
	v_mfma_f32_16x16x32_bf16 v[54:57], v[156:159], v[192:195], v[54:57]
	v_mfma_f32_16x16x32_bf16 v[50:53], v[164:167], v[192:195], v[50:53]
	v_mfma_f32_16x16x32_bf16 v[38:41], v[156:159], v[200:203], v[38:41]
	v_mfma_f32_16x16x32_bf16 v[34:37], v[164:167], v[200:203], v[34:37]
	v_mfma_f32_16x16x32_bf16 v[22:25], v[156:159], v[208:211], v[22:25]
	v_mfma_f32_16x16x32_bf16 v[18:21], v[164:167], v[208:211], v[18:21]
	v_mfma_f32_16x16x32_bf16 v[62:65], v[160:163], v[188:191], v[62:65]
	v_mfma_f32_16x16x32_bf16 v[58:61], v[168:171], v[188:191], v[58:61]
	v_mfma_f32_16x16x32_bf16 v[54:57], v[160:163], v[196:199], v[54:57]
	v_mfma_f32_16x16x32_bf16 v[50:53], v[168:171], v[196:199], v[50:53]
	v_mfma_f32_16x16x32_bf16 v[38:41], v[160:163], v[204:207], v[38:41]
	v_mfma_f32_16x16x32_bf16 v[34:37], v[168:171], v[204:207], v[34:37]
	v_mfma_f32_16x16x32_bf16 v[22:25], v[160:163], v[212:215], v[22:25]
	v_mfma_f32_16x16x32_bf16 v[18:21], v[168:171], v[212:215], v[18:21]
	s_setprio 0
	s_barrier
	s_add_u32 s22, s70, 0x40080
	s_addc_u32 s23, s71, 0
	s_add_i32 s21, s78, s9
	v_lshl_add_u64 v[156:157], s[22:23], 0, v[144:145]
	s_mov_b32 m0, s21
	s_nop 0
	global_load_lds_dwordx4 v[156:157], off
	v_lshl_add_u64 v[156:157], s[22:23], 0, v[140:141]
	s_add_i32 m0, s21, 0x2000
	s_nop 0
	global_load_lds_dwordx4 v[156:157], off
	s_waitcnt vmcnt(6)
	s_barrier
	s_setprio 1
	v_mfma_f32_16x16x32_bf16 v[46:49], v[216:219], v[172:175], v[46:49]
	v_mfma_f32_16x16x32_bf16 v[42:45], v[224:227], v[172:175], v[42:45]
	v_mfma_f32_16x16x32_bf16 v[30:33], v[216:219], v[192:195], v[30:33]
	v_mfma_f32_16x16x32_bf16 v[26:29], v[224:227], v[192:195], v[26:29]
	v_mfma_f32_16x16x32_bf16 v[14:17], v[216:219], v[200:203], v[14:17]
	v_mfma_f32_16x16x32_bf16 v[10:13], v[224:227], v[200:203], v[10:13]
	v_mfma_f32_16x16x32_bf16 v[4:7], v[216:219], v[208:211], v[4:7]
	v_mfma_f32_16x16x32_bf16 v[0:3], v[224:227], v[208:211], v[0:3]
	v_mfma_f32_16x16x32_bf16 v[46:49], v[220:223], v[188:191], v[46:49]
	v_mfma_f32_16x16x32_bf16 v[42:45], v[228:231], v[188:191], v[42:45]
	v_mfma_f32_16x16x32_bf16 v[30:33], v[220:223], v[196:199], v[30:33]
	v_mfma_f32_16x16x32_bf16 v[26:29], v[228:231], v[196:199], v[26:29]
	v_mfma_f32_16x16x32_bf16 v[14:17], v[220:223], v[204:207], v[14:17]
	v_mfma_f32_16x16x32_bf16 v[10:13], v[228:231], v[204:207], v[10:13]
	v_mfma_f32_16x16x32_bf16 v[4:7], v[220:223], v[212:215], v[4:7]
	v_mfma_f32_16x16x32_bf16 v[0:3], v[228:231], v[212:215], v[0:3]
	s_setprio 0
	s_add_i32 s20, s20, 2
	s_add_u32 vcc_lo, vcc_lo, 0x100
	s_addc_u32 vcc_hi, vcc_hi, 0
	s_add_u32 s18, s18, 0x100
	s_addc_u32 s19, s19, 0
	s_cmp_gt_u32 s20, 13
	s_barrier
	s_cbranch_scc0 .LBB0_646
; __device__ __forceinline__ unsigned pk_bf16(float a, float b) { f32x2 v = {a, b}; bf2_t r = __builtin_convertvector(v, bf2_t); return __builtin_bit_cast(unsigned, r); }
; #define PG8_WAIT_V(n) asm volatile("s_waitcnt vmcnt(" #n ")" ::: "memory")
; #define PG8_BAR __builtin_amdgcn_s_barrier()
;     __device__ __forceinline__ void operator()(const f32x4 (&acc)[2][2][4][2], const Unit& u, int wr, int wc, int fr, int fq) const {
;         const int row0 = u.pm * BM + wr * 64 + fr; int colt = u.pn * BM; bf16_t* base = O;
;         if (split_cols) { const int t = colt / split_cols; base += (size_t)t * split_stride; colt -= t * split_cols; }
;         const int col0 = colt + wc * 32 + 8 * fq;
; #pragma unroll
;         for (int ai = 0; ai < 2; ++ai)
; #pragma unroll
;             for (int m = 0; m < 4; ++m) { const int row = row0 + ai * HALF + m * 16;
;                 bf16_t* rowp = slot_stride ? base + (size_t)(colt >> 7) * slot_stride + (size_t)row * 128 + wc * 32 + 8 * fq : base + (size_t)row * ldc + col0;
; #pragma unroll
;                 for (int bj = 0; bj < 2; ++bj) { const f32x4 v0 = acc[ai][bj][m][0], v1 = acc[ai][bj][m][1];
;                     u32x4 w; w.x = pk_bf16(v0[0], v0[1]); w.y = pk_bf16(v0[2], v0[3]); w.z = pk_bf16(v1[0], v1[1]); w.w = pk_bf16(v1[2], v1[3]);
;                     *(u32x4*)(rowp + (slot_stride ? (size_t)bj * slot_stride : (size_t)bj * HALF)) = w; } }
; template <class Epi, class Sched>
; __device__ __forceinline__ void gemm_phase(LAS unsigned char* lds, const Gemm g, const Sched& S, const Epi& E) {
;     ...
;         E(acc, cur, wr, wc, fr, fq); S.done(cur);
;         if (!has_next) break;
; #pragma unroll
;         for (int a = 0; a < 2; ++a)
; #pragma unroll
;             for (int b = 0; b < 2; ++b)
; #pragma unroll
;                 for (int m = 0; m < 4; ++m)
; #pragma unroll
;                     for (int n = 0; n < 2; ++n) acc[a][b][m][n] = (f32x4){0.f, 0.f, 0.f, 0.f};
;         cur = nxt; cA = nA; cB = nB; ++ui;
;     }
;     PG8_WAIT_V(0);
;     if (wr == 0) PG8_BAR;
;     PG8_BAR;
	s_mul_hi_i32 s16, s40, 0x2e8ba2e9
	s_lshr_b32 s17, s16, 31
	s_ashr_i32 s16, s16, 1
	s_add_i32 s19, s16, s17
	s_lshl_b32 s18, s40, 8
	s_mul_i32 s16, s19, 0xbb00000
	s_mul_hi_i32 s17, s19, 0xbb00000
	s_add_u32 s16, s82, s16
	s_mulk_i32 s19, 0xf500
	s_addc_u32 s17, s83, s17
	s_add_i32 s19, s19, s18
	v_or_b32_e32 v156, s19, v153
	v_lshl_add_u32 v155, s42, 8, v9
	v_ashrrev_i32_e32 v157, 31, v156
	v_lshl_add_u64 v[156:157], v[156:157], 1, s[16:17]
	v_cvt_pk_bf16_f32 v70, v70, v71
	v_cvt_pk_bf16_f32 v71, v72, v73
	v_cvt_pk_bf16_f32 v72, v66, v67
	v_add_u32_e32 v66, 0x80, v155
	v_mad_i64_i32 v[158:159], s[16:17], v155, s81, v[156:157]
	v_cvt_pk_bf16_f32 v110, v110, v111
	v_cvt_pk_bf16_f32 v111, v112, v113
	v_cvt_pk_bf16_f32 v112, v106, v107
	v_cvt_pk_bf16_f32 v113, v108, v109
	v_or_b32_e32 v106, 16, v155
	v_mad_i64_i32 v[66:67], s[16:17], v66, s81, v[156:157]
	v_cvt_pk_bf16_f32 v46, v46, v47
	v_cvt_pk_bf16_f32 v47, v48, v49
	v_cvt_pk_bf16_f32 v48, v42, v43
	v_cvt_pk_bf16_f32 v49, v44, v45
	v_add_u32_e32 v42, 0x90, v155
	global_store_dwordx4 v[158:159], v[110:113], off offset:256
	v_cvt_pk_bf16_f32 v94, v94, v95
	v_cvt_pk_bf16_f32 v95, v96, v97
	v_mad_i64_i32 v[110:111], s[16:17], v106, s81, v[156:157]
	v_cvt_pk_bf16_f32 v96, v90, v91
	v_cvt_pk_bf16_f32 v97, v92, v93
	v_or_b32_e32 v90, 32, v155
	global_store_dwordx4 v[66:67], v[46:49], off offset:256
	v_cvt_pk_bf16_f32 v30, v30, v31
	v_cvt_pk_bf16_f32 v31, v32, v33
	v_mad_i64_i32 v[46:47], s[16:17], v42, s81, v[156:157]
	v_cvt_pk_bf16_f32 v32, v26, v27
	v_cvt_pk_bf16_f32 v33, v28, v29
	v_add_u32_e32 v26, 0xa0, v155
	global_store_dwordx4 v[110:111], v[94:97], off offset:256
	v_cvt_pk_bf16_f32 v78, v78, v79
	v_cvt_pk_bf16_f32 v79, v80, v81
	v_mad_i64_i32 v[94:95], s[16:17], v90, s81, v[156:157]
	v_cvt_pk_bf16_f32 v80, v74, v75
	v_cvt_pk_bf16_f32 v81, v76, v77
	v_or_b32_e32 v74, 48, v155
	global_store_dwordx4 v[46:47], v[30:33], off offset:256
	v_cvt_pk_bf16_f32 v14, v14, v15
	v_cvt_pk_bf16_f32 v15, v16, v17
	v_mad_i64_i32 v[30:31], s[16:17], v26, s81, v[156:157]
	v_cvt_pk_bf16_f32 v16, v10, v11
	v_cvt_pk_bf16_f32 v17, v12, v13
	v_add_u32_e32 v10, 0xb0, v155
	v_cvt_pk_bf16_f32 v126, v126, v127
	v_cvt_pk_bf16_f32 v127, v128, v129
	v_cvt_pk_bf16_f32 v128, v122, v123
	v_cvt_pk_bf16_f32 v129, v124, v125
	v_cvt_pk_bf16_f32 v106, v118, v119
	v_cvt_pk_bf16_f32 v107, v120, v121
	v_cvt_pk_bf16_f32 v108, v114, v115
	v_cvt_pk_bf16_f32 v109, v116, v117
	v_cvt_pk_bf16_f32 v90, v102, v103
	v_cvt_pk_bf16_f32 v91, v104, v105
	v_cvt_pk_bf16_f32 v92, v98, v99
	v_cvt_pk_bf16_f32 v93, v100, v101
	global_store_dwordx4 v[94:95], v[78:81], off offset:256
	v_cvt_pk_bf16_f32 v75, v88, v89
	v_cvt_pk_bf16_f32 v76, v82, v83
	v_mad_i64_i32 v[78:79], s[16:17], v74, s81, v[156:157]
	v_cvt_pk_bf16_f32 v74, v86, v87
	v_cvt_pk_bf16_f32 v77, v84, v85
	v_cvt_pk_bf16_f32 v73, v68, v69
	v_cvt_pk_bf16_f32 v62, v62, v63
	v_cvt_pk_bf16_f32 v63, v64, v65
	v_cvt_pk_bf16_f32 v64, v58, v59
	v_cvt_pk_bf16_f32 v65, v60, v61
	v_cvt_pk_bf16_f32 v42, v54, v55
	v_cvt_pk_bf16_f32 v43, v56, v57
	v_cvt_pk_bf16_f32 v44, v50, v51
	v_cvt_pk_bf16_f32 v45, v52, v53
	v_cvt_pk_bf16_f32 v26, v38, v39
	v_cvt_pk_bf16_f32 v27, v40, v41
	v_cvt_pk_bf16_f32 v28, v34, v35
	v_cvt_pk_bf16_f32 v29, v36, v37
	global_store_dwordx4 v[30:31], v[14:17], off offset:256
	v_cvt_pk_bf16_f32 v11, v24, v25
	v_cvt_pk_bf16_f32 v12, v18, v19
	v_mad_i64_i32 v[14:15], s[16:17], v10, s81, v[156:157]
	v_cvt_pk_bf16_f32 v10, v22, v23
	v_cvt_pk_bf16_f32 v13, v20, v21
	v_cvt_pk_bf16_f32 v4, v4, v5
	v_cvt_pk_bf16_f32 v5, v6, v7
	v_cvt_pk_bf16_f32 v6, v0, v1
	v_cvt_pk_bf16_f32 v7, v2, v3
	s_and_b64 vcc, exec, s[38:39]
	s_mov_b32 s40, s72
	s_mov_b32 s42, s74
	s_mov_b64 s[70:71], s[88:89]
	s_mov_b64 s[78:79], s[66:67]
	global_store_dwordx4 v[158:159], v[126:129], off
	global_store_dwordx4 v[110:111], v[106:109], off
	global_store_dwordx4 v[94:95], v[90:93], off
	global_store_dwordx4 v[78:79], v[74:77], off
	global_store_dwordx4 v[78:79], v[70:73], off offset:256
	global_store_dwordx4 v[66:67], v[62:65], off
	global_store_dwordx4 v[46:47], v[42:45], off
	global_store_dwordx4 v[30:31], v[26:29], off
	global_store_dwordx4 v[14:15], v[10:13], off
	global_store_dwordx4 v[14:15], v[4:7], off offset:256
	s_cbranch_vccz .LBB0_643
	s_waitcnt vmcnt(0)
	s_cmpk_gt_u32 s6, 0xff
	s_cbranch_scc1 .LBB0_650
	s_barrier

; #define PG8_STAGE(bufoff, gbase, voff) do { _Pragma("unroll") for (int _i = 0; _i < 2; ++_i) \
;         __builtin_amdgcn_global_load_lds((const unsigned*)((const char*)(gbase) + (voff)[_i]), (LAS unsigned*)(lds + (bufoff) + ldsw + _i * 8192), 16, 0, 0); } while (0)
; #define PG8_LDA(dst, b, h) do { _Pragma("unroll") for (int m = 0; m < 4; ++m) _Pragma("unroll") for (int k = 0; k < 2; ++k) dst[m][k] = *(const LAS bf16x8*)(lds + PG8_SA(b, h) + aoff + m * 2048 + k * 1024); } while (0)
; #define PG8_LDB(dst, b, h) do { _Pragma("unroll") for (int n = 0; n < 2; ++n) _Pragma("unroll") for (int k = 0; k < 2; ++k) dst[n][k] = *(const LAS bf16x8*)(lds + PG8_SB(b, h) + boff + n * 2048 + k * 1024); } while (0)
; #define PG8_MMA(ai, bj, At, Bt) do { __builtin_amdgcn_s_setprio(1); _Pragma("unroll") for (int m = 0; m < 4; ++m) _Pragma("unroll") for (int n = 0; n < 2; ++n) _Pragma("unroll") for (int k = 0; k < 2; ++k) \
;         acc[ai][bj][m][n] = __builtin_amdgcn_mfma_f32_16x16x32_bf16(Bt[n][k], At[m][k], acc[ai][bj][m][n], 0, 0, 0); __builtin_amdgcn_s_setprio(0); } while (0)
; #define PG8_WAIT_L(n) asm volatile("s_waitcnt lgkmcnt(" #n ")" ::: "memory")
; #define PG8_BAR __builtin_amdgcn_s_barrier()
; #define PG8_SCHED __builtin_amdgcn_sched_barrier(0)
; template <class Epi, class Sched>
; __device__ __forceinline__ void gemm_phase(LAS unsigned char* lds, const Gemm g, const Sched& S, const Epi& E) {
;     ...
;         for (int t = 0; t < nt; t += 2) {
;             const bool last = (t == nt - 2);
;             const char* a1 = cA + (size_t)(t + 1) * kstep;
;             const char* a2 = last ? nA : cA + (size_t)(t + 2) * kstep; const char* b2 = last ? nB : cB + (size_t)(t + 2) * kstep;
;             const char* a3 = a2 + kstep; const char* b3 = b2 + kstep;
;             if (last && has_next) S.a_ready(nxt);
;             PG8_LDB(B0, 0, 0); PG8_SCHED; PG8_LDA(At, 0, 0); PG8_STAGE(PG8_SA(1, 1), a1 + hstep, voffA);
;             PG8_WAIT_L(8); PG8_BAR; PG8_WAIT_L(0); PG8_MMA(0, 0, At, B0); PG8_BAR; PG8_SCHED;
;             PG8_LDB(B1, 0, 1); PG8_STAGE(PG8_SB(0, 0), b2, voffB);
;             PG8_BAR; PG8_WAIT_L(0); PG8_MMA(0, 1, At, B1); PG8_BAR;
;             PG8_LDA(At, 0, 1); PG8_STAGE(PG8_SA(0, 0), a2, voffA);
;             PG8_BAR; PG8_WAIT_L(0); PG8_MMA(1, 0, At, B0); PG8_BAR; PG8_SCHED;
.LBB0_825:
	s_add_u32 s72, s42, 0x100
	s_addc_u32 s73, s43, 0
	s_add_i32 s19, 16, 0x10000
	v_add_u32_e32 v155, s19, v152
	ds_read_b128 v[156:159], v155
	ds_read_b128 v[160:163], v155 offset:1024
	ds_read_b128 v[164:167], v155 offset:2048
	ds_read_b128 v[168:171], v155 offset:3072
	s_cmp_eq_u32 s18, 40
	s_cselect_b32 s71, s41, s73
	s_cselect_b32 s70, s40, s72
	s_cselect_b32 s67, s1, s17
	s_cselect_b32 s66, s0, s16
	v_lshl_add_u64 v[216:217], s[42:43], 0, v[148:149]
	s_add_i32 m0, s11, 0xc000
	ds_read_b128 v[172:175], v154
	ds_read_b128 v[188:191], v154 offset:1024
	ds_read_b128 v[192:195], v154 offset:2048
	ds_read_b128 v[196:199], v154 offset:3072
	ds_read_b128 v[200:203], v154 offset:4096
	ds_read_b128 v[204:207], v154 offset:5120
	ds_read_b128 v[208:211], v154 offset:6144
	ds_read_b128 v[212:215], v154 offset:7168
	global_load_lds_dwordx4 v[216:217], off
	v_lshl_add_u64 v[216:217], s[42:43], 0, v[150:151]
	s_add_i32 m0, s11, 0xe000
	s_nop 0
	global_load_lds_dwordx4 v[216:217], off
	s_barrier
	s_waitcnt lgkmcnt(0)
	s_setprio 1
	s_waitcnt lgkmcnt(0)
	v_mfma_f32_16x16x32_bf16 v[126:129], v[156:159], v[172:175], v[126:129]
	v_mfma_f32_16x16x32_bf16 v[122:125], v[164:167], v[172:175], v[122:125]
	v_mfma_f32_16x16x32_bf16 v[118:121], v[156:159], v[192:195], v[118:121]
	v_mfma_f32_16x16x32_bf16 v[114:117], v[164:167], v[192:195], v[114:117]
	v_mfma_f32_16x16x32_bf16 v[102:105], v[156:159], v[200:203], v[102:105]
	v_mfma_f32_16x16x32_bf16 v[98:101], v[164:167], v[200:203], v[98:101]
	v_mfma_f32_16x16x32_bf16 v[86:89], v[156:159], v[208:211], v[86:89]
	v_mfma_f32_16x16x32_bf16 v[82:85], v[164:167], v[208:211], v[82:85]
	v_mfma_f32_16x16x32_bf16 v[126:129], v[160:163], v[188:191], v[126:129]
	v_mfma_f32_16x16x32_bf16 v[122:125], v[168:171], v[188:191], v[122:125]
	v_mfma_f32_16x16x32_bf16 v[118:121], v[160:163], v[196:199], v[118:121]
	v_mfma_f32_16x16x32_bf16 v[114:117], v[168:171], v[196:199], v[114:117]
	v_mfma_f32_16x16x32_bf16 v[102:105], v[160:163], v[204:207], v[102:105]
	v_mfma_f32_16x16x32_bf16 v[98:101], v[168:171], v[204:207], v[98:101]
	v_mfma_f32_16x16x32_bf16 v[86:89], v[160:163], v[212:215], v[86:89]
	v_mfma_f32_16x16x32_bf16 v[82:85], v[168:171], v[212:215], v[82:85]
	s_setprio 0
	s_barrier
	s_add_i32 s22, 16, 0x14000
	s_add_i32 s19, s19, s9
	v_add_u32_e32 v155, s22, v152
	v_lshl_add_u64 v[232:233], s[66:67], 0, v[144:145]
	s_mov_b32 m0, s19
	ds_read_b128 v[216:219], v155
	ds_read_b128 v[220:223], v155 offset:1024
	ds_read_b128 v[224:227], v155 offset:2048
	ds_read_b128 v[228:231], v155 offset:3072
	global_load_lds_dwordx4 v[232:233], off
	v_lshl_add_u64 v[234:235], s[66:67], 0, v[140:141]
	s_add_i32 m0, s19, 0x2000
	s_nop 0
	global_load_lds_dwordx4 v[234:235], off
	s_barrier
	s_waitcnt lgkmcnt(0)
	s_setprio 1
	s_waitcnt lgkmcnt(0)
	v_mfma_f32_16x16x32_bf16 v[110:113], v[216:219], v[172:175], v[110:113]
	v_mfma_f32_16x16x32_bf16 v[106:109], v[224:227], v[172:175], v[106:109]
	v_mfma_f32_16x16x32_bf16 v[94:97], v[216:219], v[192:195], v[94:97]
	v_mfma_f32_16x16x32_bf16 v[90:93], v[224:227], v[192:195], v[90:93]
	v_mfma_f32_16x16x32_bf16 v[78:81], v[216:219], v[200:203], v[78:81]
	v_mfma_f32_16x16x32_bf16 v[74:77], v[224:227], v[200:203], v[74:77]
	v_mfma_f32_16x16x32_bf16 v[70:73], v[216:219], v[208:211], v[70:73]
	v_mfma_f32_16x16x32_bf16 v[66:69], v[224:227], v[208:211], v[66:69]
	v_mfma_f32_16x16x32_bf16 v[110:113], v[220:223], v[188:191], v[110:113]
	v_mfma_f32_16x16x32_bf16 v[106:109], v[228:231], v[188:191], v[106:109]
	v_mfma_f32_16x16x32_bf16 v[94:97], v[220:223], v[196:199], v[94:97]
	v_mfma_f32_16x16x32_bf16 v[90:93], v[228:231], v[196:199], v[90:93]
	v_mfma_f32_16x16x32_bf16 v[78:81], v[220:223], v[204:207], v[78:81]
	v_mfma_f32_16x16x32_bf16 v[74:77], v[228:231], v[204:207], v[74:77]
	v_mfma_f32_16x16x32_bf16 v[70:73], v[220:223], v[212:215], v[70:73]
	v_mfma_f32_16x16x32_bf16 v[66:69], v[228:231], v[212:215], v[66:69]
	s_setprio 0
	s_mov_b32 m0, s11
	v_lshl_add_u64 v[236:237], s[70:71], 0, v[146:147]
	s_barrier
	ds_read_b128 v[172:175], v154 offset:16384
	ds_read_b128 v[188:191], v154 offset:17408
	ds_read_b128 v[192:195], v154 offset:18432
	ds_read_b128 v[196:199], v154 offset:19456
	ds_read_b128 v[200:203], v154 offset:20480
	ds_read_b128 v[204:207], v154 offset:21504
	ds_read_b128 v[208:211], v154 offset:22528
	ds_read_b128 v[212:215], v154 offset:23552
	global_load_lds_dwordx4 v[236:237], off
	v_lshl_add_u64 v[238:239], s[70:71], 0, v[142:143]
	s_mov_b32 m0, s74
	s_nop 0
	global_load_lds_dwordx4 v[238:239], off
	s_barrier
	s_waitcnt lgkmcnt(0)
	s_setprio 1
	s_waitcnt lgkmcnt(0)
	v_mfma_f32_16x16x32_bf16 v[62:65], v[156:159], v[172:175], v[62:65]
	v_mfma_f32_16x16x32_bf16 v[58:61], v[164:167], v[172:175], v[58:61]
	v_mfma_f32_16x16x32_bf16 v[54:57], v[156:159], v[192:195], v[54:57]
	v_mfma_f32_16x16x32_bf16 v[50:53], v[164:167], v[192:195], v[50:53]
	v_mfma_f32_16x16x32_bf16 v[38:41], v[156:159], v[200:203], v[38:41]
	v_mfma_f32_16x16x32_bf16 v[34:37], v[164:167], v[200:203], v[34:37]
	v_mfma_f32_16x16x32_bf16 v[22:25], v[156:159], v[208:211], v[22:25]
	v_mfma_f32_16x16x32_bf16 v[18:21], v[164:167], v[208:211], v[18:21]
	v_mfma_f32_16x16x32_bf16 v[62:65], v[160:163], v[188:191], v[62:65]
	v_mfma_f32_16x16x32_bf16 v[58:61], v[168:171], v[188:191], v[58:61]
	v_mfma_f32_16x16x32_bf16 v[54:57], v[160:163], v[196:199], v[54:57]
	v_mfma_f32_16x16x32_bf16 v[50:53], v[168:171], v[196:199], v[50:53]
	v_mfma_f32_16x16x32_bf16 v[38:41], v[160:163], v[204:207], v[38:41]
	v_mfma_f32_16x16x32_bf16 v[34:37], v[168:171], v[204:207], v[34:37]
	v_mfma_f32_16x16x32_bf16 v[22:25], v[160:163], v[212:215], v[22:25]
	v_mfma_f32_16x16x32_bf16 v[18:21], v[168:171], v[212:215], v[18:21]
	s_setprio 0
	s_barrier
; #define PG8_STAGE(bufoff, gbase, voff) do { _Pragma("unroll") for (int _i = 0; _i < 2; ++_i) \
;         __builtin_amdgcn_global_load_lds((const unsigned*)((const char*)(gbase) + (voff)[_i]), (LAS unsigned*)(lds + (bufoff) + ldsw + _i * 8192), 16, 0, 0); } while (0)
; #define PG8_LDA(dst, b, h) do { _Pragma("unroll") for (int m = 0; m < 4; ++m) _Pragma("unroll") for (int k = 0; k < 2; ++k) dst[m][k] = *(const LAS bf16x8*)(lds + PG8_SA(b, h) + aoff + m * 2048 + k * 1024); } while (0)
; #define PG8_LDB(dst, b, h) do { _Pragma("unroll") for (int n = 0; n < 2; ++n) _Pragma("unroll") for (int k = 0; k < 2; ++k) dst[n][k] = *(const LAS bf16x8*)(lds + PG8_SB(b, h) + boff + n * 2048 + k * 1024); } while (0)
; #define PG8_MMA(ai, bj, At, Bt) do { __builtin_amdgcn_s_setprio(1); _Pragma("unroll") for (int m = 0; m < 4; ++m) _Pragma("unroll") for (int n = 0; n < 2; ++n) _Pragma("unroll") for (int k = 0; k < 2; ++k) \
;         acc[ai][bj][m][n] = __builtin_amdgcn_mfma_f32_16x16x32_bf16(Bt[n][k], At[m][k], acc[ai][bj][m][n], 0, 0, 0); __builtin_amdgcn_s_setprio(0); } while (0)
; #define PG8_WAIT_V(n) asm volatile("s_waitcnt vmcnt(" #n ")" ::: "memory")
; #define PG8_WAIT_L(n) asm volatile("s_waitcnt lgkmcnt(" #n ")" ::: "memory")
; #define PG8_BAR __builtin_amdgcn_s_barrier()
; #define PG8_SCHED __builtin_amdgcn_sched_barrier(0)
; template <class Epi, class Sched>
; __device__ __forceinline__ void gemm_phase(LAS unsigned char* lds, const Gemm g, const Sched& S, const Epi& E) {
;     ...
;             PG8_STAGE(PG8_SB(0, 1), b2 + hstep, voffB);
;             PG8_WAIT_V(6); PG8_BAR; PG8_MMA(1, 1, At, B1); PG8_BAR;
;             PG8_LDB(B0, 1, 0); PG8_SCHED; PG8_LDA(At, 1, 0); PG8_STAGE(PG8_SA(0, 1), a2 + hstep, voffA);
;             PG8_WAIT_L(8); PG8_BAR; PG8_WAIT_L(0); PG8_MMA(0, 0, At, B0); PG8_BAR; PG8_SCHED;
;             PG8_LDB(B1, 1, 1); PG8_STAGE(PG8_SB(1, 0), b3, voffB);
;             PG8_BAR; PG8_WAIT_L(0); PG8_MMA(0, 1, At, B1); PG8_BAR;
;             PG8_LDA(At, 1, 1); PG8_STAGE(PG8_SA(1, 0), a3, voffA);
	s_add_u32 s20, s66, 0xb0000
	s_addc_u32 s21, s67, 0
	s_add_i32 s19, s22, s9
	v_lshl_add_u64 v[156:157], s[20:21], 0, v[144:145]
	s_mov_b32 m0, s19
	s_nop 0
	global_load_lds_dwordx4 v[156:157], off
	v_lshl_add_u64 v[156:157], s[20:21], 0, v[140:141]
	s_add_i32 m0, s19, 0x2000
	s_nop 0
	global_load_lds_dwordx4 v[156:157], off
	s_waitcnt vmcnt(6)
	s_barrier
	s_setprio 1
	v_mfma_f32_16x16x32_bf16 v[46:49], v[216:219], v[172:175], v[46:49]
	v_mfma_f32_16x16x32_bf16 v[42:45], v[224:227], v[172:175], v[42:45]
	v_mfma_f32_16x16x32_bf16 v[30:33], v[216:219], v[192:195], v[30:33]
	v_mfma_f32_16x16x32_bf16 v[26:29], v[224:227], v[192:195], v[26:29]
	v_mfma_f32_16x16x32_bf16 v[14:17], v[216:219], v[200:203], v[14:17]
	v_mfma_f32_16x16x32_bf16 v[10:13], v[224:227], v[200:203], v[10:13]
	v_mfma_f32_16x16x32_bf16 v[4:7], v[216:219], v[208:211], v[4:7]
	v_mfma_f32_16x16x32_bf16 v[0:3], v[224:227], v[208:211], v[0:3]
	v_mfma_f32_16x16x32_bf16 v[46:49], v[220:223], v[188:191], v[46:49]
	v_mfma_f32_16x16x32_bf16 v[42:45], v[228:231], v[188:191], v[42:45]
	v_mfma_f32_16x16x32_bf16 v[30:33], v[220:223], v[196:199], v[30:33]
	v_mfma_f32_16x16x32_bf16 v[26:29], v[228:231], v[196:199], v[26:29]
	v_mfma_f32_16x16x32_bf16 v[14:17], v[220:223], v[204:207], v[14:17]
	v_mfma_f32_16x16x32_bf16 v[10:13], v[228:231], v[204:207], v[10:13]
	v_mfma_f32_16x16x32_bf16 v[4:7], v[220:223], v[212:215], v[4:7]
	v_mfma_f32_16x16x32_bf16 v[0:3], v[228:231], v[212:215], v[0:3]
	s_setprio 0
	s_add_i32 s19, 16, 0x18000
	v_add_u32_e32 v155, s19, v152
	s_barrier
	ds_read_b128 v[156:159], v155
	ds_read_b128 v[160:163], v155 offset:1024
	ds_read_b128 v[164:167], v155 offset:2048
	ds_read_b128 v[168:171], v155 offset:3072
	s_add_u32 s20, s70, 0xb0000
	s_addc_u32 s21, s71, 0
	s_mov_b32 m0, s12
	v_lshl_add_u64 v[216:217], s[20:21], 0, v[146:147]
	ds_read_b128 v[172:175], v154 offset:32768
	ds_read_b128 v[188:191], v154 offset:33792
	ds_read_b128 v[192:195], v154 offset:34816
	ds_read_b128 v[196:199], v154 offset:35840
	ds_read_b128 v[200:203], v154 offset:36864
	ds_read_b128 v[204:207], v154 offset:37888
	ds_read_b128 v[208:211], v154 offset:38912
	ds_read_b128 v[212:215], v154 offset:39936
	global_load_lds_dwordx4 v[216:217], off
	v_lshl_add_u64 v[216:217], s[20:21], 0, v[142:143]
	s_mov_b32 m0, s13
	s_nop 0
	global_load_lds_dwordx4 v[216:217], off
	s_barrier
	s_waitcnt lgkmcnt(0)
	s_setprio 1
	s_waitcnt lgkmcnt(0)
	v_mfma_f32_16x16x32_bf16 v[126:129], v[156:159], v[172:175], v[126:129]
	v_mfma_f32_16x16x32_bf16 v[122:125], v[164:167], v[172:175], v[122:125]
	v_mfma_f32_16x16x32_bf16 v[118:121], v[156:159], v[192:195], v[118:121]
	v_mfma_f32_16x16x32_bf16 v[114:117], v[164:167], v[192:195], v[114:117]
	v_mfma_f32_16x16x32_bf16 v[102:105], v[156:159], v[200:203], v[102:105]
	v_mfma_f32_16x16x32_bf16 v[98:101], v[164:167], v[200:203], v[98:101]
	v_mfma_f32_16x16x32_bf16 v[86:89], v[156:159], v[208:211], v[86:89]
	v_mfma_f32_16x16x32_bf16 v[82:85], v[164:167], v[208:211], v[82:85]
	v_mfma_f32_16x16x32_bf16 v[126:129], v[160:163], v[188:191], v[126:129]
	v_mfma_f32_16x16x32_bf16 v[122:125], v[168:171], v[188:191], v[122:125]
	v_mfma_f32_16x16x32_bf16 v[118:121], v[160:163], v[196:199], v[118:121]
	v_mfma_f32_16x16x32_bf16 v[114:117], v[168:171], v[196:199], v[114:117]
	v_mfma_f32_16x16x32_bf16 v[102:105], v[160:163], v[204:207], v[102:105]
	v_mfma_f32_16x16x32_bf16 v[98:101], v[168:171], v[204:207], v[98:101]
	v_mfma_f32_16x16x32_bf16 v[86:89], v[160:163], v[212:215], v[86:89]
	v_mfma_f32_16x16x32_bf16 v[82:85], v[168:171], v[212:215], v[82:85]
	s_setprio 0
	s_barrier
	s_add_i32 s22, 16, 0x1c000
	s_add_i32 s19, s19, s9
	v_add_u32_e32 v155, s22, v152
	v_lshl_add_u64 v[232:233], v[232:233], 0, s[94:95]
	s_mov_b32 m0, s19
	ds_read_b128 v[216:219], v155
	ds_read_b128 v[220:223], v155 offset:1024
	ds_read_b128 v[224:227], v155 offset:2048
	ds_read_b128 v[228:231], v155 offset:3072
	global_load_lds_dwordx4 v[232:233], off
	v_lshl_add_u64 v[232:233], v[234:235], 0, s[94:95]
	s_add_i32 m0, s19, 0x2000
	s_nop 0
	global_load_lds_dwordx4 v[232:233], off
	s_barrier
	s_waitcnt lgkmcnt(0)
	s_setprio 1
	s_waitcnt lgkmcnt(0)
	v_mfma_f32_16x16x32_bf16 v[110:113], v[216:219], v[172:175], v[110:113]
	v_mfma_f32_16x16x32_bf16 v[106:109], v[224:227], v[172:175], v[106:109]
	v_mfma_f32_16x16x32_bf16 v[94:97], v[216:219], v[192:195], v[94:97]
	v_mfma_f32_16x16x32_bf16 v[90:93], v[224:227], v[192:195], v[90:93]
	v_mfma_f32_16x16x32_bf16 v[78:81], v[216:219], v[200:203], v[78:81]
	v_mfma_f32_16x16x32_bf16 v[74:77], v[224:227], v[200:203], v[74:77]
	v_mfma_f32_16x16x32_bf16 v[70:73], v[216:219], v[208:211], v[70:73]
	v_mfma_f32_16x16x32_bf16 v[66:69], v[224:227], v[208:211], v[66:69]
	v_mfma_f32_16x16x32_bf16 v[110:113], v[220:223], v[188:191], v[110:113]
	v_mfma_f32_16x16x32_bf16 v[106:109], v[228:231], v[188:191], v[106:109]
	v_mfma_f32_16x16x32_bf16 v[94:97], v[220:223], v[196:199], v[94:97]
	v_mfma_f32_16x16x32_bf16 v[90:93], v[228:231], v[196:199], v[90:93]
	v_mfma_f32_16x16x32_bf16 v[78:81], v[220:223], v[204:207], v[78:81]
	v_mfma_f32_16x16x32_bf16 v[74:77], v[228:231], v[204:207], v[74:77]
	v_mfma_f32_16x16x32_bf16 v[70:73], v[220:223], v[212:215], v[70:73]
	v_mfma_f32_16x16x32_bf16 v[66:69], v[228:231], v[212:215], v[66:69]
	s_setprio 0
	s_mov_b32 m0, s14
	v_lshl_add_u64 v[232:233], v[236:237], 0, s[94:95]
	s_barrier
	ds_read_b128 v[172:175], v154 offset:49152
	ds_read_b128 v[188:191], v154 offset:50176
	ds_read_b128 v[192:195], v154 offset:51200
	ds_read_b128 v[196:199], v154 offset:52224
	ds_read_b128 v[200:203], v154 offset:53248
	ds_read_b128 v[204:207], v154 offset:54272
	ds_read_b128 v[208:211], v154 offset:55296
	ds_read_b128 v[212:215], v154 offset:56320
	global_load_lds_dwordx4 v[232:233], off
	v_lshl_add_u64 v[232:233], v[238:239], 0, s[94:95]
	s_mov_b32 m0, s15
	s_nop 0
	global_load_lds_dwordx4 v[232:233], off
	s_barrier
; #define PG8_STAGE(bufoff, gbase, voff) do { _Pragma("unroll") for (int _i = 0; _i < 2; ++_i) \
;         __builtin_amdgcn_global_load_lds((const unsigned*)((const char*)(gbase) + (voff)[_i]), (LAS unsigned*)(lds + (bufoff) + ldsw + _i * 8192), 16, 0, 0); } while (0)
; #define PG8_MMA(ai, bj, At, Bt) do { __builtin_amdgcn_s_setprio(1); _Pragma("unroll") for (int m = 0; m < 4; ++m) _Pragma("unroll") for (int n = 0; n < 2; ++n) _Pragma("unroll") for (int k = 0; k < 2; ++k) \
;         acc[ai][bj][m][n] = __builtin_amdgcn_mfma_f32_16x16x32_bf16(Bt[n][k], At[m][k], acc[ai][bj][m][n], 0, 0, 0); __builtin_amdgcn_s_setprio(0); } while (0)
; #define PG8_WAIT_V(n) asm volatile("s_waitcnt vmcnt(" #n ")" ::: "memory")
; #define PG8_WAIT_L(n) asm volatile("s_waitcnt lgkmcnt(" #n ")" ::: "memory")
; #define PG8_BAR __builtin_amdgcn_s_barrier()
; #define PG8_SCHED __builtin_amdgcn_sched_barrier(0)
; template <class Epi, class Sched>
; __device__ __forceinline__ void gemm_phase(LAS unsigned char* lds, const Gemm g, const Sched& S, const Epi& E) {
;     ...
;             PG8_BAR; PG8_WAIT_L(0); PG8_MMA(1, 0, At, B0); PG8_BAR; PG8_SCHED;
;             PG8_STAGE(PG8_SB(1, 1), b3 + hstep, voffB);
;             PG8_WAIT_V(6); PG8_BAR; PG8_MMA(1, 1, At, B1); PG8_BAR;
	s_waitcnt lgkmcnt(0)
	s_setprio 1
	s_waitcnt lgkmcnt(0)
	v_mfma_f32_16x16x32_bf16 v[62:65], v[156:159], v[172:175], v[62:65]
	v_mfma_f32_16x16x32_bf16 v[58:61], v[164:167], v[172:175], v[58:61]
	v_mfma_f32_16x16x32_bf16 v[54:57], v[156:159], v[192:195], v[54:57]
	v_mfma_f32_16x16x32_bf16 v[50:53], v[164:167], v[192:195], v[50:53]
	v_mfma_f32_16x16x32_bf16 v[38:41], v[156:159], v[200:203], v[38:41]
	v_mfma_f32_16x16x32_bf16 v[34:37], v[164:167], v[200:203], v[34:37]
	v_mfma_f32_16x16x32_bf16 v[22:25], v[156:159], v[208:211], v[22:25]
	v_mfma_f32_16x16x32_bf16 v[18:21], v[164:167], v[208:211], v[18:21]
	v_mfma_f32_16x16x32_bf16 v[62:65], v[160:163], v[188:191], v[62:65]
	v_mfma_f32_16x16x32_bf16 v[58:61], v[168:171], v[188:191], v[58:61]
	v_mfma_f32_16x16x32_bf16 v[54:57], v[160:163], v[196:199], v[54:57]
	v_mfma_f32_16x16x32_bf16 v[50:53], v[168:171], v[196:199], v[50:53]
	v_mfma_f32_16x16x32_bf16 v[38:41], v[160:163], v[204:207], v[38:41]
	v_mfma_f32_16x16x32_bf16 v[34:37], v[168:171], v[204:207], v[34:37]
	v_mfma_f32_16x16x32_bf16 v[22:25], v[160:163], v[212:215], v[22:25]
	v_mfma_f32_16x16x32_bf16 v[18:21], v[168:171], v[212:215], v[18:21]
	s_setprio 0
	s_barrier
	s_add_u32 s20, s66, 0xb0080
	s_addc_u32 s21, s67, 0
	s_add_i32 s19, s22, s9
	v_lshl_add_u64 v[156:157], s[20:21], 0, v[144:145]
	s_mov_b32 m0, s19
	s_nop 0
	global_load_lds_dwordx4 v[156:157], off
	v_lshl_add_u64 v[156:157], s[20:21], 0, v[140:141]
	s_add_i32 m0, s19, 0x2000
	s_nop 0
	global_load_lds_dwordx4 v[156:157], off
	s_waitcnt vmcnt(6)
	s_barrier
	s_setprio 1
	v_mfma_f32_16x16x32_bf16 v[46:49], v[216:219], v[172:175], v[46:49]
	v_mfma_f32_16x16x32_bf16 v[42:45], v[224:227], v[172:175], v[42:45]
	v_mfma_f32_16x16x32_bf16 v[30:33], v[216:219], v[192:195], v[30:33]
	v_mfma_f32_16x16x32_bf16 v[26:29], v[224:227], v[192:195], v[26:29]
	v_mfma_f32_16x16x32_bf16 v[14:17], v[216:219], v[200:203], v[14:17]
	v_mfma_f32_16x16x32_bf16 v[10:13], v[224:227], v[200:203], v[10:13]
	v_mfma_f32_16x16x32_bf16 v[4:7], v[216:219], v[208:211], v[4:7]
	v_mfma_f32_16x16x32_bf16 v[0:3], v[224:227], v[208:211], v[0:3]
	v_mfma_f32_16x16x32_bf16 v[46:49], v[220:223], v[188:191], v[46:49]
	v_mfma_f32_16x16x32_bf16 v[42:45], v[228:231], v[188:191], v[42:45]
	v_mfma_f32_16x16x32_bf16 v[30:33], v[220:223], v[196:199], v[30:33]
	v_mfma_f32_16x16x32_bf16 v[26:29], v[228:231], v[196:199], v[26:29]
	v_mfma_f32_16x16x32_bf16 v[14:17], v[220:223], v[204:207], v[14:17]
	v_mfma_f32_16x16x32_bf16 v[10:13], v[228:231], v[204:207], v[10:13]
	v_mfma_f32_16x16x32_bf16 v[4:7], v[220:223], v[212:215], v[4:7]
	v_mfma_f32_16x16x32_bf16 v[0:3], v[228:231], v[212:215], v[0:3]
	s_setprio 0
	s_add_i32 s18, s18, 2
	s_add_u32 s16, s16, 0x100
	s_addc_u32 s17, s17, 0
	s_cmp_gt_u32 s18, 41
	s_mov_b64 s[42:43], s[72:73]
	s_barrier
	s_cbranch_scc0 .LBB0_825
; __device__ __forceinline__ unsigned pk_bf16(float a, float b) { f32x2 v = {a, b}; bf2_t r = __builtin_convertvector(v, bf2_t); return __builtin_bit_cast(unsigned, r); }
; #define PG8_WAIT_V(n) asm volatile("s_waitcnt vmcnt(" #n ")" ::: "memory")
; #define PG8_BAR __builtin_amdgcn_s_barrier()
;     __device__ __forceinline__ void operator()(const f32x4 (&acc)[2][2][4][2], const Unit& u, int wr, int wc, int fr, int fq) const {
;         const int row0 = u.pm * BM + wr * 64 + fr; int colt = u.pn * BM; bf16_t* base = O;
;         if (split_cols) { const int t = colt / split_cols; base += (size_t)t * split_stride; colt -= t * split_cols; }
;         const int col0 = colt + wc * 32 + 8 * fq;
; #pragma unroll
;         for (int ai = 0; ai < 2; ++ai)
; #pragma unroll
;             for (int m = 0; m < 4; ++m) { const int row = row0 + ai * HALF + m * 16;
;                 bf16_t* rowp = slot_stride ? base + (size_t)(colt >> 7) * slot_stride + (size_t)row * 128 + wc * 32 + 8 * fq : base + (size_t)row * ldc + col0;
; #pragma unroll
;                 for (int bj = 0; bj < 2; ++bj) { const f32x4 v0 = acc[ai][bj][m][0], v1 = acc[ai][bj][m][1];
;                     u32x4 w; w.x = pk_bf16(v0[0], v0[1]); w.y = pk_bf16(v0[2], v0[3]); w.z = pk_bf16(v1[0], v1[1]); w.w = pk_bf16(v1[2], v1[3]);
;                     *(u32x4*)(rowp + (slot_stride ? (size_t)bj * slot_stride : (size_t)bj * HALF)) = w; } }
; template <class Epi, class Sched>
; __device__ __forceinline__ void gemm_phase(LAS unsigned char* lds, const Gemm g, const Sched& S, const Epi& E) {
;     ...
;         E(acc, cur, wr, wc, fr, fq); S.done(cur);
;         if (!has_next) break;
; #pragma unroll
;         for (int a = 0; a < 2; ++a)
; #pragma unroll
;             for (int b = 0; b < 2; ++b)
; #pragma unroll
;                 for (int m = 0; m < 4; ++m)
; #pragma unroll
;                     for (int n = 0; n < 2; ++n) acc[a][b][m][n] = (f32x4){0.f, 0.f, 0.f, 0.f};
;         cur = nxt; cA = nA; cB = nB; ++ui;
;     }
;     PG8_WAIT_V(0);
;     if (wr == 0) PG8_BAR;
;     PG8_BAR;
	v_lshl_add_u32 v156, s78, 8, v9
	v_lshl_or_b32 v158, s75, 8, v153
	v_readlane_b32 s16, v244, 38
	v_ashrrev_i32_e32 v159, 31, v158
	v_readlane_b32 s17, v244, 39
	v_ashrrev_i32_e32 v157, 31, v156
	v_lshlrev_b64 v[160:161], 11, v[156:157]
	v_lshl_add_u64 v[158:159], v[158:159], 1, s[16:17]
	v_lshl_add_u64 v[160:161], v[158:159], 0, v[160:161]
	s_mov_b64 s[16:17], 0x40000
	v_cvt_pk_bf16_f32 v70, v70, v71
	v_cvt_pk_bf16_f32 v71, v72, v73
	v_cvt_pk_bf16_f32 v72, v66, v67
	v_lshl_add_u64 v[66:67], v[160:161], 0, s[16:17]
	s_mov_b32 s16, 0x40000
	v_cvt_pk_bf16_f32 v62, v62, v63
	v_cvt_pk_bf16_f32 v63, v64, v65
	v_cvt_pk_bf16_f32 v64, v58, v59
	v_add_co_u32_e32 v58, vcc, s16, v160
	v_cvt_pk_bf16_f32 v46, v46, v47
	v_cvt_pk_bf16_f32 v47, v48, v49
	v_cvt_pk_bf16_f32 v48, v42, v43
	v_cvt_pk_bf16_f32 v49, v44, v45
	s_mov_b64 s[16:17], 0x48000
	v_addc_co_u32_e32 v59, vcc, 0, v161, vcc
	global_store_dwordx4 v[66:67], v[46:49], off offset:256
	v_cvt_pk_bf16_f32 v30, v30, v31
	v_cvt_pk_bf16_f32 v31, v32, v33
	v_lshl_add_u64 v[46:47], v[160:161], 0, s[16:17]
	s_mov_b32 s16, 0x48000
	v_add_co_u32_e32 v48, vcc, s16, v160
	v_cvt_pk_bf16_f32 v32, v26, v27
	v_cvt_pk_bf16_f32 v33, v28, v29
	s_mov_b64 s[16:17], 0x50000
	v_cvt_pk_bf16_f32 v110, v110, v111
	v_cvt_pk_bf16_f32 v111, v112, v113
	v_cvt_pk_bf16_f32 v112, v106, v107
	v_or_b32_e32 v106, 16, v156
	v_addc_co_u32_e32 v49, vcc, 0, v161, vcc
	global_store_dwordx4 v[46:47], v[30:33], off offset:256
	v_ashrrev_i32_e32 v107, 31, v106
	v_cvt_pk_bf16_f32 v94, v94, v95
	v_lshl_add_u64 v[30:31], v[160:161], 0, s[16:17]
	s_mov_b32 s16, 0x50000
	v_cvt_pk_bf16_f32 v95, v96, v97
	v_cvt_pk_bf16_f32 v96, v90, v91
	v_or_b32_e32 v90, 32, v156
	v_add_co_u32_e32 v32, vcc, s16, v160
	v_cvt_pk_bf16_f32 v14, v14, v15
	v_cvt_pk_bf16_f32 v15, v16, v17
	v_cvt_pk_bf16_f32 v16, v10, v11
	v_cvt_pk_bf16_f32 v17, v12, v13
	s_mov_b64 s[16:17], 0x58000
	v_cvt_pk_bf16_f32 v113, v108, v109
	v_lshlrev_b64 v[106:107], 11, v[106:107]
	v_ashrrev_i32_e32 v91, 31, v90
	v_cvt_pk_bf16_f32 v78, v78, v79
	v_cvt_pk_bf16_f32 v79, v80, v81
	v_cvt_pk_bf16_f32 v80, v74, v75
	v_or_b32_e32 v74, 48, v156
	v_addc_co_u32_e32 v33, vcc, 0, v161, vcc
	global_store_dwordx4 v[30:31], v[14:17], off offset:256
	global_store_dwordx4 v[160:161], v[110:113], off offset:256
	v_cvt_pk_bf16_f32 v97, v92, v93
	v_lshl_add_u64 v[14:15], v[160:161], 0, s[16:17]
	s_mov_b32 s16, 0x58000
	v_lshl_add_u64 v[110:111], v[158:159], 0, v[106:107]
	v_lshlrev_b64 v[90:91], 11, v[90:91]
	v_ashrrev_i32_e32 v75, 31, v74
	v_add_co_u32_e32 v16, vcc, s16, v160
	global_store_dwordx4 v[110:111], v[94:97], off offset:256
	v_cvt_pk_bf16_f32 v81, v76, v77
	v_lshlrev_b64 v[74:75], 11, v[74:75]
	v_lshl_add_u64 v[94:95], v[158:159], 0, v[90:91]
	v_addc_co_u32_e32 v17, vcc, 0, v161, vcc
	v_readlane_b32 s70, v244, 55
	v_cvt_pk_bf16_f32 v126, v126, v127
	v_cvt_pk_bf16_f32 v127, v128, v129
	v_cvt_pk_bf16_f32 v128, v122, v123
	v_cvt_pk_bf16_f32 v129, v124, v125
	v_cvt_pk_bf16_f32 v106, v118, v119
	v_cvt_pk_bf16_f32 v107, v120, v121
	v_cvt_pk_bf16_f32 v108, v114, v115
	v_cvt_pk_bf16_f32 v109, v116, v117
	v_cvt_pk_bf16_f32 v90, v102, v103
	v_cvt_pk_bf16_f32 v91, v104, v105
	v_cvt_pk_bf16_f32 v92, v98, v99
	v_cvt_pk_bf16_f32 v93, v100, v101
	global_store_dwordx4 v[94:95], v[78:81], off offset:256
	v_cvt_pk_bf16_f32 v76, v82, v83
	v_cvt_pk_bf16_f32 v77, v84, v85
	v_lshl_add_u64 v[78:79], v[158:159], 0, v[74:75]
	v_cvt_pk_bf16_f32 v74, v86, v87
	v_cvt_pk_bf16_f32 v75, v88, v89
	v_cvt_pk_bf16_f32 v73, v68, v69
	v_cvt_pk_bf16_f32 v65, v60, v61
	v_cvt_pk_bf16_f32 v42, v54, v55
	v_cvt_pk_bf16_f32 v43, v56, v57
	v_cvt_pk_bf16_f32 v44, v50, v51
	v_cvt_pk_bf16_f32 v45, v52, v53
	v_cvt_pk_bf16_f32 v26, v38, v39
	v_cvt_pk_bf16_f32 v27, v40, v41
	v_cvt_pk_bf16_f32 v28, v34, v35
	v_cvt_pk_bf16_f32 v29, v36, v37
	v_cvt_pk_bf16_f32 v10, v22, v23
	v_cvt_pk_bf16_f32 v11, v24, v25
	v_cvt_pk_bf16_f32 v12, v18, v19
	v_cvt_pk_bf16_f32 v13, v20, v21
	v_cvt_pk_bf16_f32 v4, v4, v5
	v_cvt_pk_bf16_f32 v5, v6, v7
	v_cvt_pk_bf16_f32 v6, v0, v1
	v_cvt_pk_bf16_f32 v7, v2, v3
	s_and_b64 vcc, exec, s[38:39]
	s_mov_b32 s75, s85
	s_mov_b32 s78, s88
	s_mov_b64 s[72:73], s[0:1]
	s_mov_b64 s[42:43], s[40:41]
	v_readlane_b32 s71, v244, 56
	global_store_dwordx4 v[160:161], v[126:129], off
	global_store_dwordx4 v[110:111], v[106:109], off
	global_store_dwordx4 v[94:95], v[90:93], off
	global_store_dwordx4 v[78:79], v[74:77], off
	global_store_dwordx4 v[78:79], v[70:73], off offset:256
	global_store_dwordx4 v[58:59], v[62:65], off
	global_store_dwordx4 v[48:49], v[42:45], off
	global_store_dwordx4 v[32:33], v[26:29], off
	global_store_dwordx4 v[16:17], v[10:13], off
	global_store_dwordx4 v[14:15], v[4:7], off offset:256
	s_cbranch_vccz .LBB0_818
	s_waitcnt vmcnt(0)
	v_readlane_b32 s16, v244, 51
	s_cmpk_gt_u32 s6, 0xff
	v_readlane_b32 s17, v244, 52
	s_cbranch_scc1 .LBB0_829
	s_barrier
